# parameter variant: GEMM barrier behind the first 6 MFMAs of each block instead of 4
# speedup vs baseline: 1.0040x; 1.0040x over previous
.LBB0_168:
	s_add_u32 s46, s66, 0xfff80080
	s_addc_u32 s47, s67, -1
	s_add_i32 s62, 0, 0x10000
	s_cmp_eq_u32 s82, 28
	s_cselect_b32 s69, s17, s47
	s_cselect_b32 s68, s65, s46
	v_add_u32_e32 v143, s62, v140
	s_cselect_b32 s61, s13, s81
	s_cselect_b32 s60, s79, s80
	s_add_i32 s63, 0, 0x14000
	ds_read_b128 v[144:147], v143
	ds_read_b128 v[148:151], v143 offset:1024
	ds_read_b128 v[152:155], v143 offset:2048
	ds_read_b128 v[156:159], v143 offset:3072
	v_add_u32_e32 v143, s63, v140
	ds_read_b128 v[160:163], v143
	ds_read_b128 v[178:181], v143 offset:1024
	ds_read_b128 v[182:185], v143 offset:2048
	ds_read_b128 v[186:189], v143 offset:3072
	v_lshl_add_u64 v[164:165], s[66:67], 0, v[136:137]
	s_add_i32 m0, s19, 0xc000
	ds_read_b128 v[206:209], v142
	ds_read_b128 v[210:213], v142 offset:1024
	ds_read_b128 v[214:217], v142 offset:2048
	ds_read_b128 v[218:221], v142 offset:3072
	ds_read_b128 v[222:225], v142 offset:4096
	ds_read_b128 v[226:229], v142 offset:5120
	ds_read_b128 v[230:233], v142 offset:6144
	ds_read_b128 v[234:237], v142 offset:7168
	global_load_lds_dwordx4 v[164:165], off
	v_lshl_add_u64 v[164:165], s[66:67], 0, v[138:139]
	s_add_i32 m0, s19, 0xe000
	s_nop 0
	global_load_lds_dwordx4 v[164:165], off
	s_waitcnt vmcnt(8)
	s_waitcnt lgkmcnt(0)
	s_setprio 1
	s_waitcnt lgkmcnt(0)
	v_mfma_f32_16x16x32_bf16 v[126:129], v[144:147], v[206:209], v[126:129]
	v_mfma_f32_16x16x32_bf16 v[122:125], v[152:155], v[206:209], v[122:125]
	v_mfma_f32_16x16x32_bf16 v[118:121], v[144:147], v[214:217], v[118:121]
	v_mfma_f32_16x16x32_bf16 v[114:117], v[152:155], v[214:217], v[114:117]
	v_mfma_f32_16x16x32_bf16 v[102:105], v[144:147], v[222:225], v[102:105]
	v_mfma_f32_16x16x32_bf16 v[98:101], v[152:155], v[222:225], v[98:101]
	s_barrier
	v_mfma_f32_16x16x32_bf16 v[86:89], v[144:147], v[230:233], v[86:89]
	v_mfma_f32_16x16x32_bf16 v[82:85], v[152:155], v[230:233], v[82:85]
	v_mfma_f32_16x16x32_bf16 v[126:129], v[148:151], v[210:213], v[126:129]
	v_mfma_f32_16x16x32_bf16 v[122:125], v[156:159], v[210:213], v[122:125]
	v_mfma_f32_16x16x32_bf16 v[118:121], v[148:151], v[218:221], v[118:121]
	v_mfma_f32_16x16x32_bf16 v[114:117], v[156:159], v[218:221], v[114:117]
	v_mfma_f32_16x16x32_bf16 v[102:105], v[148:151], v[226:229], v[102:105]
	v_mfma_f32_16x16x32_bf16 v[98:101], v[156:159], v[226:229], v[98:101]
	v_mfma_f32_16x16x32_bf16 v[86:89], v[148:151], v[234:237], v[86:89]
	v_mfma_f32_16x16x32_bf16 v[82:85], v[156:159], v[234:237], v[82:85]
	v_mfma_f32_16x16x32_bf16 v[110:113], v[160:163], v[206:209], v[110:113]
	v_mfma_f32_16x16x32_bf16 v[106:109], v[182:185], v[206:209], v[106:109]
	v_mfma_f32_16x16x32_bf16 v[94:97], v[160:163], v[214:217], v[94:97]
	v_mfma_f32_16x16x32_bf16 v[90:93], v[182:185], v[214:217], v[90:93]
	v_mfma_f32_16x16x32_bf16 v[78:81], v[160:163], v[222:225], v[78:81]
	v_mfma_f32_16x16x32_bf16 v[74:77], v[182:185], v[222:225], v[74:77]
	v_mfma_f32_16x16x32_bf16 v[70:73], v[160:163], v[230:233], v[70:73]
	v_mfma_f32_16x16x32_bf16 v[66:69], v[182:185], v[230:233], v[66:69]
	v_mfma_f32_16x16x32_bf16 v[110:113], v[178:181], v[210:213], v[110:113]
	v_mfma_f32_16x16x32_bf16 v[106:109], v[186:189], v[210:213], v[106:109]
	v_mfma_f32_16x16x32_bf16 v[94:97], v[178:181], v[218:221], v[94:97]
	v_mfma_f32_16x16x32_bf16 v[90:93], v[186:189], v[218:221], v[90:93]
	v_mfma_f32_16x16x32_bf16 v[78:81], v[178:181], v[226:229], v[78:81]
	v_mfma_f32_16x16x32_bf16 v[74:77], v[186:189], v[226:229], v[74:77]
	v_mfma_f32_16x16x32_bf16 v[70:73], v[178:181], v[234:237], v[70:73]
	v_mfma_f32_16x16x32_bf16 v[66:69], v[186:189], v[234:237], v[66:69]
	s_barrier
	s_setprio 0
	s_add_i32 s46, s62, s71
	v_lshl_add_u64 v[164:165], s[60:61], 0, v[166:167]
	s_mov_b32 m0, s46
	ds_read_b128 v[206:209], v142 offset:16384
	ds_read_b128 v[210:213], v142 offset:17408
	ds_read_b128 v[214:217], v142 offset:18432
	ds_read_b128 v[218:221], v142 offset:19456
	ds_read_b128 v[222:225], v142 offset:20480
	ds_read_b128 v[226:229], v142 offset:21504
	ds_read_b128 v[230:233], v142 offset:22528
	ds_read_b128 v[234:237], v142 offset:23552
	global_load_lds_dwordx4 v[164:165], off
	s_add_i32 m0, s46, 0x2000
	s_add_u32 s46, s60, 0x80000
	v_lshl_add_u64 v[242:243], s[60:61], 0, v[130:131]
	s_addc_u32 s47, s61, 0
	s_add_i32 s62, s63, s71
	global_load_lds_dwordx4 v[242:243], off
	v_lshl_add_u64 v[244:245], s[46:47], 0, v[166:167]
	s_mov_b32 m0, s62
	v_lshl_add_u64 v[246:247], s[68:69], 0, v[132:133]
	global_load_lds_dwordx4 v[244:245], off
	v_lshl_add_u64 v[244:245], s[46:47], 0, v[130:131]
	s_add_i32 m0, s62, 0x2000
	s_nop 0
	global_load_lds_dwordx4 v[244:245], off
	v_lshl_add_u64 v[244:245], s[68:69], 0, v[134:135]
	s_mov_b32 m0, s19
	s_nop 0
	global_load_lds_dwordx4 v[244:245], off
	s_mov_b32 m0, s73
	s_nop 0
	global_load_lds_dwordx4 v[246:247], off
	s_waitcnt vmcnt(8)
	s_waitcnt lgkmcnt(0)
	s_setprio 1
	s_waitcnt lgkmcnt(0)
	v_mfma_f32_16x16x32_bf16 v[62:65], v[144:147], v[206:209], v[62:65]
	v_mfma_f32_16x16x32_bf16 v[58:61], v[152:155], v[206:209], v[58:61]
	v_mfma_f32_16x16x32_bf16 v[54:57], v[144:147], v[214:217], v[54:57]
	v_mfma_f32_16x16x32_bf16 v[50:53], v[152:155], v[214:217], v[50:53]
	v_mfma_f32_16x16x32_bf16 v[38:41], v[144:147], v[222:225], v[38:41]
	v_mfma_f32_16x16x32_bf16 v[34:37], v[152:155], v[222:225], v[34:37]
	s_barrier
	v_mfma_f32_16x16x32_bf16 v[22:25], v[144:147], v[230:233], v[22:25]
	v_mfma_f32_16x16x32_bf16 v[18:21], v[152:155], v[230:233], v[18:21]
	v_mfma_f32_16x16x32_bf16 v[62:65], v[148:151], v[210:213], v[62:65]
	v_mfma_f32_16x16x32_bf16 v[58:61], v[156:159], v[210:213], v[58:61]
	v_mfma_f32_16x16x32_bf16 v[54:57], v[148:151], v[218:221], v[54:57]
	v_mfma_f32_16x16x32_bf16 v[50:53], v[156:159], v[218:221], v[50:53]
	v_mfma_f32_16x16x32_bf16 v[38:41], v[148:151], v[226:229], v[38:41]
	v_mfma_f32_16x16x32_bf16 v[34:37], v[156:159], v[226:229], v[34:37]
	v_mfma_f32_16x16x32_bf16 v[22:25], v[148:151], v[234:237], v[22:25]
	v_mfma_f32_16x16x32_bf16 v[18:21], v[156:159], v[234:237], v[18:21]
	v_mfma_f32_16x16x32_bf16 v[46:49], v[160:163], v[206:209], v[46:49]
	v_mfma_f32_16x16x32_bf16 v[42:45], v[182:185], v[206:209], v[42:45]
	v_mfma_f32_16x16x32_bf16 v[30:33], v[160:163], v[214:217], v[30:33]
	v_mfma_f32_16x16x32_bf16 v[26:29], v[182:185], v[214:217], v[26:29]
	v_mfma_f32_16x16x32_bf16 v[14:17], v[160:163], v[222:225], v[14:17]
	v_mfma_f32_16x16x32_bf16 v[10:13], v[182:185], v[222:225], v[10:13]
	v_mfma_f32_16x16x32_bf16 v[6:9], v[160:163], v[230:233], v[6:9]
	v_mfma_f32_16x16x32_bf16 v[2:5], v[182:185], v[230:233], v[2:5]
	v_mfma_f32_16x16x32_bf16 v[46:49], v[178:181], v[210:213], v[46:49]
	v_mfma_f32_16x16x32_bf16 v[42:45], v[186:189], v[210:213], v[42:45]
	v_mfma_f32_16x16x32_bf16 v[30:33], v[178:181], v[218:221], v[30:33]
	v_mfma_f32_16x16x32_bf16 v[26:29], v[186:189], v[218:221], v[26:29]
	v_mfma_f32_16x16x32_bf16 v[14:17], v[178:181], v[226:229], v[14:17]
	v_mfma_f32_16x16x32_bf16 v[10:13], v[186:189], v[226:229], v[10:13]
	v_mfma_f32_16x16x32_bf16 v[6:9], v[178:181], v[234:237], v[6:9]
	v_mfma_f32_16x16x32_bf16 v[2:5], v[186:189], v[234:237], v[2:5]
	s_barrier
	s_setprio 0
	s_add_i32 s62, 0, 0x18000
	v_add_u32_e32 v143, s62, v140
	s_add_i32 s63, 0, 0x1c000
	ds_read_b128 v[144:147], v143
	ds_read_b128 v[148:151], v143 offset:1024
	ds_read_b128 v[152:155], v143 offset:2048
	ds_read_b128 v[156:159], v143 offset:3072
	v_add_u32_e32 v143, s63, v140
	ds_read_b128 v[160:163], v143
	ds_read_b128 v[178:181], v143 offset:1024
	ds_read_b128 v[182:185], v143 offset:2048
	ds_read_b128 v[186:189], v143 offset:3072
	s_add_u32 s46, s68, 0x80000
	s_addc_u32 s47, s69, 0
	s_mov_b32 m0, s74
	v_lshl_add_u64 v[248:249], s[46:47], 0, v[134:135]
	ds_read_b128 v[206:209], v142 offset:32768
	ds_read_b128 v[210:213], v142 offset:33792
	ds_read_b128 v[214:217], v142 offset:34816
	ds_read_b128 v[218:221], v142 offset:35840
	ds_read_b128 v[222:225], v142 offset:36864
	ds_read_b128 v[226:229], v142 offset:37888
	ds_read_b128 v[230:233], v142 offset:38912
	ds_read_b128 v[234:237], v142 offset:39936
	global_load_lds_dwordx4 v[248:249], off
	v_lshl_add_u64 v[248:249], s[46:47], 0, v[132:133]
	s_mov_b32 m0, s75
	s_nop 0
	global_load_lds_dwordx4 v[248:249], off
	s_waitcnt vmcnt(8)
	s_waitcnt lgkmcnt(0)
	s_setprio 1
	s_waitcnt lgkmcnt(0)
	v_mfma_f32_16x16x32_bf16 v[126:129], v[144:147], v[206:209], v[126:129]
	v_mfma_f32_16x16x32_bf16 v[122:125], v[152:155], v[206:209], v[122:125]
	v_mfma_f32_16x16x32_bf16 v[118:121], v[144:147], v[214:217], v[118:121]
	v_mfma_f32_16x16x32_bf16 v[114:117], v[152:155], v[214:217], v[114:117]
	v_mfma_f32_16x16x32_bf16 v[102:105], v[144:147], v[222:225], v[102:105]
	v_mfma_f32_16x16x32_bf16 v[98:101], v[152:155], v[222:225], v[98:101]
	s_barrier
	v_mfma_f32_16x16x32_bf16 v[86:89], v[144:147], v[230:233], v[86:89]
	v_mfma_f32_16x16x32_bf16 v[82:85], v[152:155], v[230:233], v[82:85]
	v_mfma_f32_16x16x32_bf16 v[126:129], v[148:151], v[210:213], v[126:129]
	v_mfma_f32_16x16x32_bf16 v[122:125], v[156:159], v[210:213], v[122:125]
	v_mfma_f32_16x16x32_bf16 v[118:121], v[148:151], v[218:221], v[118:121]
	v_mfma_f32_16x16x32_bf16 v[114:117], v[156:159], v[218:221], v[114:117]
	v_mfma_f32_16x16x32_bf16 v[102:105], v[148:151], v[226:229], v[102:105]
	v_mfma_f32_16x16x32_bf16 v[98:101], v[156:159], v[226:229], v[98:101]
	v_mfma_f32_16x16x32_bf16 v[86:89], v[148:151], v[234:237], v[86:89]
	v_mfma_f32_16x16x32_bf16 v[82:85], v[156:159], v[234:237], v[82:85]
	v_mfma_f32_16x16x32_bf16 v[110:113], v[160:163], v[206:209], v[110:113]
	v_mfma_f32_16x16x32_bf16 v[106:109], v[182:185], v[206:209], v[106:109]
	v_mfma_f32_16x16x32_bf16 v[94:97], v[160:163], v[214:217], v[94:97]
	v_mfma_f32_16x16x32_bf16 v[90:93], v[182:185], v[214:217], v[90:93]
	v_mfma_f32_16x16x32_bf16 v[78:81], v[160:163], v[222:225], v[78:81]
	v_mfma_f32_16x16x32_bf16 v[74:77], v[182:185], v[222:225], v[74:77]
	v_mfma_f32_16x16x32_bf16 v[70:73], v[160:163], v[230:233], v[70:73]
	v_mfma_f32_16x16x32_bf16 v[66:69], v[182:185], v[230:233], v[66:69]
	v_mfma_f32_16x16x32_bf16 v[110:113], v[178:181], v[210:213], v[110:113]
	v_mfma_f32_16x16x32_bf16 v[106:109], v[186:189], v[210:213], v[106:109]
	v_mfma_f32_16x16x32_bf16 v[94:97], v[178:181], v[218:221], v[94:97]
	v_mfma_f32_16x16x32_bf16 v[90:93], v[186:189], v[218:221], v[90:93]
	v_mfma_f32_16x16x32_bf16 v[78:81], v[178:181], v[226:229], v[78:81]
	v_mfma_f32_16x16x32_bf16 v[74:77], v[186:189], v[226:229], v[74:77]
	v_mfma_f32_16x16x32_bf16 v[70:73], v[178:181], v[234:237], v[70:73]
	v_mfma_f32_16x16x32_bf16 v[66:69], v[186:189], v[234:237], v[66:69]
	s_barrier
	s_setprio 0
	s_add_i32 s46, s62, s71
	v_lshl_add_u64 v[164:165], v[164:165], 0, s[42:43]
	s_mov_b32 m0, s46
	ds_read_b128 v[206:209], v142 offset:49152
	ds_read_b128 v[210:213], v142 offset:50176
	ds_read_b128 v[214:217], v142 offset:51200
	ds_read_b128 v[218:221], v142 offset:52224
	ds_read_b128 v[222:225], v142 offset:53248
	ds_read_b128 v[226:229], v142 offset:54272
	ds_read_b128 v[230:233], v142 offset:55296
	ds_read_b128 v[234:237], v142 offset:56320
	global_load_lds_dwordx4 v[164:165], off
	s_add_i32 m0, s46, 0x2000
	s_add_u32 s46, s60, 0x80080
	v_lshl_add_u64 v[164:165], v[242:243], 0, s[42:43]
	s_addc_u32 s47, s61, 0
	s_add_i32 s60, s63, s71
	global_load_lds_dwordx4 v[164:165], off
	v_lshl_add_u64 v[164:165], s[46:47], 0, v[166:167]
	s_mov_b32 m0, s60
	s_nop 0
	global_load_lds_dwordx4 v[164:165], off
	v_lshl_add_u64 v[164:165], s[46:47], 0, v[130:131]
	s_add_i32 m0, s60, 0x2000
	s_nop 0
	global_load_lds_dwordx4 v[164:165], off
	v_lshl_add_u64 v[164:165], v[244:245], 0, s[42:43]
	s_mov_b32 m0, s76
	s_nop 0
	global_load_lds_dwordx4 v[164:165], off
	v_lshl_add_u64 v[164:165], v[246:247], 0, s[42:43]
	s_mov_b32 m0, s77
	s_nop 0
	global_load_lds_dwordx4 v[164:165], off
	s_waitcnt vmcnt(8)
	s_waitcnt lgkmcnt(0)
	s_setprio 1
	s_waitcnt lgkmcnt(0)
	v_mfma_f32_16x16x32_bf16 v[62:65], v[144:147], v[206:209], v[62:65]
	v_mfma_f32_16x16x32_bf16 v[58:61], v[152:155], v[206:209], v[58:61]
	v_mfma_f32_16x16x32_bf16 v[54:57], v[144:147], v[214:217], v[54:57]
	v_mfma_f32_16x16x32_bf16 v[50:53], v[152:155], v[214:217], v[50:53]
	v_mfma_f32_16x16x32_bf16 v[38:41], v[144:147], v[222:225], v[38:41]
	v_mfma_f32_16x16x32_bf16 v[34:37], v[152:155], v[222:225], v[34:37]
	s_barrier
	v_mfma_f32_16x16x32_bf16 v[22:25], v[144:147], v[230:233], v[22:25]
	v_mfma_f32_16x16x32_bf16 v[18:21], v[152:155], v[230:233], v[18:21]
	v_mfma_f32_16x16x32_bf16 v[62:65], v[148:151], v[210:213], v[62:65]
	v_mfma_f32_16x16x32_bf16 v[58:61], v[156:159], v[210:213], v[58:61]
	v_mfma_f32_16x16x32_bf16 v[54:57], v[148:151], v[218:221], v[54:57]
	v_mfma_f32_16x16x32_bf16 v[50:53], v[156:159], v[218:221], v[50:53]
	v_mfma_f32_16x16x32_bf16 v[38:41], v[148:151], v[226:229], v[38:41]
	v_mfma_f32_16x16x32_bf16 v[34:37], v[156:159], v[226:229], v[34:37]
	v_mfma_f32_16x16x32_bf16 v[22:25], v[148:151], v[234:237], v[22:25]
	v_mfma_f32_16x16x32_bf16 v[18:21], v[156:159], v[234:237], v[18:21]
	v_mfma_f32_16x16x32_bf16 v[46:49], v[160:163], v[206:209], v[46:49]
	v_mfma_f32_16x16x32_bf16 v[42:45], v[182:185], v[206:209], v[42:45]
	v_mfma_f32_16x16x32_bf16 v[30:33], v[160:163], v[214:217], v[30:33]
	v_mfma_f32_16x16x32_bf16 v[26:29], v[182:185], v[214:217], v[26:29]
	v_mfma_f32_16x16x32_bf16 v[14:17], v[160:163], v[222:225], v[14:17]
	v_mfma_f32_16x16x32_bf16 v[10:13], v[182:185], v[222:225], v[10:13]
	v_mfma_f32_16x16x32_bf16 v[6:9], v[160:163], v[230:233], v[6:9]
	v_mfma_f32_16x16x32_bf16 v[2:5], v[182:185], v[230:233], v[2:5]
	v_mfma_f32_16x16x32_bf16 v[46:49], v[178:181], v[210:213], v[46:49]
	v_mfma_f32_16x16x32_bf16 v[42:45], v[186:189], v[210:213], v[42:45]
	v_mfma_f32_16x16x32_bf16 v[30:33], v[178:181], v[218:221], v[30:33]
	v_mfma_f32_16x16x32_bf16 v[26:29], v[186:189], v[218:221], v[26:29]
	v_mfma_f32_16x16x32_bf16 v[14:17], v[178:181], v[226:229], v[14:17]
	v_mfma_f32_16x16x32_bf16 v[10:13], v[186:189], v[226:229], v[10:13]
	v_mfma_f32_16x16x32_bf16 v[6:9], v[178:181], v[234:237], v[6:9]
	v_mfma_f32_16x16x32_bf16 v[2:5], v[186:189], v[234:237], v[2:5]
	s_barrier
	s_setprio 0
	s_add_i32 s82, s82, 2
	s_add_u32 s66, s66, 0x100
	s_addc_u32 s67, s67, 0
	s_add_u32 s80, s80, 0x100
	s_addc_u32 s81, s81, 0
	s_cmp_gt_u32 s82, 29
	s_cbranch_scc0 .LBB0_168
	s_and_b64 vcc, exec, s[10:11]
	s_cbranch_vccz .LBB0_171
	s_barrier

.LBB0_426:
	s_add_u32 s46, s66, 0xfffe0080
	s_addc_u32 s47, s67, -1
	s_add_i32 s62, 0, 0x10000
	s_cmp_eq_u32 s84, 4
	s_cselect_b32 s69, s19, s47
	s_cselect_b32 s68, s80, s46
	v_add_u32_e32 v143, s62, v140
	s_cselect_b32 s61, s17, s83
	s_cselect_b32 s60, s81, s82
	s_add_i32 s63, 0, 0x14000
	ds_read_b128 v[144:147], v143
	ds_read_b128 v[148:151], v143 offset:1024
	ds_read_b128 v[152:155], v143 offset:2048
	ds_read_b128 v[156:159], v143 offset:3072
	v_add_u32_e32 v143, s63, v140
	ds_read_b128 v[160:163], v143
	ds_read_b128 v[178:181], v143 offset:1024
	ds_read_b128 v[182:185], v143 offset:2048
	ds_read_b128 v[186:189], v143 offset:3072
	v_lshl_add_u64 v[164:165], s[66:67], 0, v[136:137]
	s_add_i32 m0, s11, 0xc000
	ds_read_b128 v[206:209], v142
	ds_read_b128 v[210:213], v142 offset:1024
	ds_read_b128 v[214:217], v142 offset:2048
	ds_read_b128 v[218:221], v142 offset:3072
	ds_read_b128 v[222:225], v142 offset:4096
	ds_read_b128 v[226:229], v142 offset:5120
	ds_read_b128 v[230:233], v142 offset:6144
	ds_read_b128 v[234:237], v142 offset:7168
	global_load_lds_dwordx4 v[164:165], off
	v_lshl_add_u64 v[164:165], s[66:67], 0, v[138:139]
	s_add_i32 m0, s11, 0xe000
	s_nop 0
	global_load_lds_dwordx4 v[164:165], off
	s_waitcnt vmcnt(8)
	s_waitcnt lgkmcnt(0)
	s_setprio 1
	s_waitcnt lgkmcnt(0)
	v_mfma_f32_16x16x32_bf16 v[126:129], v[144:147], v[206:209], v[126:129]
	v_mfma_f32_16x16x32_bf16 v[122:125], v[152:155], v[206:209], v[122:125]
	v_mfma_f32_16x16x32_bf16 v[118:121], v[144:147], v[214:217], v[118:121]
	v_mfma_f32_16x16x32_bf16 v[114:117], v[152:155], v[214:217], v[114:117]
	v_mfma_f32_16x16x32_bf16 v[102:105], v[144:147], v[222:225], v[102:105]
	v_mfma_f32_16x16x32_bf16 v[98:101], v[152:155], v[222:225], v[98:101]
	s_barrier
	v_mfma_f32_16x16x32_bf16 v[86:89], v[144:147], v[230:233], v[86:89]
	v_mfma_f32_16x16x32_bf16 v[82:85], v[152:155], v[230:233], v[82:85]
	v_mfma_f32_16x16x32_bf16 v[126:129], v[148:151], v[210:213], v[126:129]
	v_mfma_f32_16x16x32_bf16 v[122:125], v[156:159], v[210:213], v[122:125]
	v_mfma_f32_16x16x32_bf16 v[118:121], v[148:151], v[218:221], v[118:121]
	v_mfma_f32_16x16x32_bf16 v[114:117], v[156:159], v[218:221], v[114:117]
	v_mfma_f32_16x16x32_bf16 v[102:105], v[148:151], v[226:229], v[102:105]
	v_mfma_f32_16x16x32_bf16 v[98:101], v[156:159], v[226:229], v[98:101]
	v_mfma_f32_16x16x32_bf16 v[86:89], v[148:151], v[234:237], v[86:89]
	v_mfma_f32_16x16x32_bf16 v[82:85], v[156:159], v[234:237], v[82:85]
	v_mfma_f32_16x16x32_bf16 v[110:113], v[160:163], v[206:209], v[110:113]
	v_mfma_f32_16x16x32_bf16 v[106:109], v[182:185], v[206:209], v[106:109]
	v_mfma_f32_16x16x32_bf16 v[94:97], v[160:163], v[214:217], v[94:97]
	v_mfma_f32_16x16x32_bf16 v[90:93], v[182:185], v[214:217], v[90:93]
	v_mfma_f32_16x16x32_bf16 v[78:81], v[160:163], v[222:225], v[78:81]
	v_mfma_f32_16x16x32_bf16 v[74:77], v[182:185], v[222:225], v[74:77]
	v_mfma_f32_16x16x32_bf16 v[70:73], v[160:163], v[230:233], v[70:73]
	v_mfma_f32_16x16x32_bf16 v[66:69], v[182:185], v[230:233], v[66:69]
	v_mfma_f32_16x16x32_bf16 v[110:113], v[178:181], v[210:213], v[110:113]
	v_mfma_f32_16x16x32_bf16 v[106:109], v[186:189], v[210:213], v[106:109]
	v_mfma_f32_16x16x32_bf16 v[94:97], v[178:181], v[218:221], v[94:97]
	v_mfma_f32_16x16x32_bf16 v[90:93], v[186:189], v[218:221], v[90:93]
	v_mfma_f32_16x16x32_bf16 v[78:81], v[178:181], v[226:229], v[78:81]
	v_mfma_f32_16x16x32_bf16 v[74:77], v[186:189], v[226:229], v[74:77]
	v_mfma_f32_16x16x32_bf16 v[70:73], v[178:181], v[234:237], v[70:73]
	v_mfma_f32_16x16x32_bf16 v[66:69], v[186:189], v[234:237], v[66:69]
	s_barrier
	s_setprio 0
	s_add_i32 s46, s62, s72
	v_lshl_add_u64 v[164:165], s[60:61], 0, v[166:167]
	s_mov_b32 m0, s46
	ds_read_b128 v[206:209], v142 offset:16384
	ds_read_b128 v[210:213], v142 offset:17408
	ds_read_b128 v[214:217], v142 offset:18432
	ds_read_b128 v[218:221], v142 offset:19456
	ds_read_b128 v[222:225], v142 offset:20480
	ds_read_b128 v[226:229], v142 offset:21504
	ds_read_b128 v[230:233], v142 offset:22528
	ds_read_b128 v[234:237], v142 offset:23552
	global_load_lds_dwordx4 v[164:165], off
	s_add_i32 m0, s46, 0x2000
	s_add_u32 s46, s60, 0x20000
	v_lshl_add_u64 v[242:243], s[60:61], 0, v[130:131]
	s_addc_u32 s47, s61, 0
	s_add_i32 s62, s63, s72
	global_load_lds_dwordx4 v[242:243], off
	v_lshl_add_u64 v[244:245], s[46:47], 0, v[166:167]
	s_mov_b32 m0, s62
	v_lshl_add_u64 v[246:247], s[68:69], 0, v[132:133]
	global_load_lds_dwordx4 v[244:245], off
	v_lshl_add_u64 v[244:245], s[46:47], 0, v[130:131]
	s_add_i32 m0, s62, 0x2000
	s_nop 0
	global_load_lds_dwordx4 v[244:245], off
	v_lshl_add_u64 v[244:245], s[68:69], 0, v[134:135]
	s_mov_b32 m0, s11
	s_nop 0
	global_load_lds_dwordx4 v[244:245], off
	s_mov_b32 m0, s74
	s_nop 0
	global_load_lds_dwordx4 v[246:247], off
	s_waitcnt vmcnt(8)
	s_waitcnt lgkmcnt(0)
	s_setprio 1
	s_waitcnt lgkmcnt(0)
	v_mfma_f32_16x16x32_bf16 v[62:65], v[144:147], v[206:209], v[62:65]
	v_mfma_f32_16x16x32_bf16 v[58:61], v[152:155], v[206:209], v[58:61]
	v_mfma_f32_16x16x32_bf16 v[54:57], v[144:147], v[214:217], v[54:57]
	v_mfma_f32_16x16x32_bf16 v[50:53], v[152:155], v[214:217], v[50:53]
	v_mfma_f32_16x16x32_bf16 v[38:41], v[144:147], v[222:225], v[38:41]
	v_mfma_f32_16x16x32_bf16 v[34:37], v[152:155], v[222:225], v[34:37]
	s_barrier
	v_mfma_f32_16x16x32_bf16 v[22:25], v[144:147], v[230:233], v[22:25]
	v_mfma_f32_16x16x32_bf16 v[18:21], v[152:155], v[230:233], v[18:21]
	v_mfma_f32_16x16x32_bf16 v[62:65], v[148:151], v[210:213], v[62:65]
	v_mfma_f32_16x16x32_bf16 v[58:61], v[156:159], v[210:213], v[58:61]
	v_mfma_f32_16x16x32_bf16 v[54:57], v[148:151], v[218:221], v[54:57]
	v_mfma_f32_16x16x32_bf16 v[50:53], v[156:159], v[218:221], v[50:53]
	v_mfma_f32_16x16x32_bf16 v[38:41], v[148:151], v[226:229], v[38:41]
	v_mfma_f32_16x16x32_bf16 v[34:37], v[156:159], v[226:229], v[34:37]
	v_mfma_f32_16x16x32_bf16 v[22:25], v[148:151], v[234:237], v[22:25]
	v_mfma_f32_16x16x32_bf16 v[18:21], v[156:159], v[234:237], v[18:21]
	v_mfma_f32_16x16x32_bf16 v[46:49], v[160:163], v[206:209], v[46:49]
	v_mfma_f32_16x16x32_bf16 v[42:45], v[182:185], v[206:209], v[42:45]
	v_mfma_f32_16x16x32_bf16 v[30:33], v[160:163], v[214:217], v[30:33]
	v_mfma_f32_16x16x32_bf16 v[26:29], v[182:185], v[214:217], v[26:29]
	v_mfma_f32_16x16x32_bf16 v[14:17], v[160:163], v[222:225], v[14:17]
	v_mfma_f32_16x16x32_bf16 v[10:13], v[182:185], v[222:225], v[10:13]
	v_mfma_f32_16x16x32_bf16 v[6:9], v[160:163], v[230:233], v[6:9]
	v_mfma_f32_16x16x32_bf16 v[2:5], v[182:185], v[230:233], v[2:5]
	v_mfma_f32_16x16x32_bf16 v[46:49], v[178:181], v[210:213], v[46:49]
	v_mfma_f32_16x16x32_bf16 v[42:45], v[186:189], v[210:213], v[42:45]
	v_mfma_f32_16x16x32_bf16 v[30:33], v[178:181], v[218:221], v[30:33]
	v_mfma_f32_16x16x32_bf16 v[26:29], v[186:189], v[218:221], v[26:29]
	v_mfma_f32_16x16x32_bf16 v[14:17], v[178:181], v[226:229], v[14:17]
	v_mfma_f32_16x16x32_bf16 v[10:13], v[186:189], v[226:229], v[10:13]
	v_mfma_f32_16x16x32_bf16 v[6:9], v[178:181], v[234:237], v[6:9]
	v_mfma_f32_16x16x32_bf16 v[2:5], v[186:189], v[234:237], v[2:5]
	s_barrier
	s_setprio 0
	s_add_i32 s62, 0, 0x18000
	v_add_u32_e32 v143, s62, v140
	s_add_i32 s63, 0, 0x1c000
	ds_read_b128 v[144:147], v143
	ds_read_b128 v[148:151], v143 offset:1024
	ds_read_b128 v[152:155], v143 offset:2048
	ds_read_b128 v[156:159], v143 offset:3072
	v_add_u32_e32 v143, s63, v140
	ds_read_b128 v[160:163], v143
	ds_read_b128 v[178:181], v143 offset:1024
	ds_read_b128 v[182:185], v143 offset:2048
	ds_read_b128 v[186:189], v143 offset:3072
	s_add_u32 s46, s68, 0x20000
	s_addc_u32 s47, s69, 0
	s_mov_b32 m0, s75
	v_lshl_add_u64 v[248:249], s[46:47], 0, v[134:135]
	ds_read_b128 v[206:209], v142 offset:32768
	ds_read_b128 v[210:213], v142 offset:33792
	ds_read_b128 v[214:217], v142 offset:34816
	ds_read_b128 v[218:221], v142 offset:35840
	ds_read_b128 v[222:225], v142 offset:36864
	ds_read_b128 v[226:229], v142 offset:37888
	ds_read_b128 v[230:233], v142 offset:38912
	ds_read_b128 v[234:237], v142 offset:39936
	global_load_lds_dwordx4 v[248:249], off
	v_lshl_add_u64 v[248:249], s[46:47], 0, v[132:133]
	s_mov_b32 m0, s76
	s_nop 0
	global_load_lds_dwordx4 v[248:249], off
	s_waitcnt vmcnt(8)
	s_waitcnt lgkmcnt(0)
	s_setprio 1
	s_waitcnt lgkmcnt(0)
	v_mfma_f32_16x16x32_bf16 v[126:129], v[144:147], v[206:209], v[126:129]
	v_mfma_f32_16x16x32_bf16 v[122:125], v[152:155], v[206:209], v[122:125]
	v_mfma_f32_16x16x32_bf16 v[118:121], v[144:147], v[214:217], v[118:121]
	v_mfma_f32_16x16x32_bf16 v[114:117], v[152:155], v[214:217], v[114:117]
	v_mfma_f32_16x16x32_bf16 v[102:105], v[144:147], v[222:225], v[102:105]
	v_mfma_f32_16x16x32_bf16 v[98:101], v[152:155], v[222:225], v[98:101]
	s_barrier
	v_mfma_f32_16x16x32_bf16 v[86:89], v[144:147], v[230:233], v[86:89]
	v_mfma_f32_16x16x32_bf16 v[82:85], v[152:155], v[230:233], v[82:85]
	v_mfma_f32_16x16x32_bf16 v[126:129], v[148:151], v[210:213], v[126:129]
	v_mfma_f32_16x16x32_bf16 v[122:125], v[156:159], v[210:213], v[122:125]
	v_mfma_f32_16x16x32_bf16 v[118:121], v[148:151], v[218:221], v[118:121]
	v_mfma_f32_16x16x32_bf16 v[114:117], v[156:159], v[218:221], v[114:117]
	v_mfma_f32_16x16x32_bf16 v[102:105], v[148:151], v[226:229], v[102:105]
	v_mfma_f32_16x16x32_bf16 v[98:101], v[156:159], v[226:229], v[98:101]
	v_mfma_f32_16x16x32_bf16 v[86:89], v[148:151], v[234:237], v[86:89]
	v_mfma_f32_16x16x32_bf16 v[82:85], v[156:159], v[234:237], v[82:85]
	v_mfma_f32_16x16x32_bf16 v[110:113], v[160:163], v[206:209], v[110:113]
	v_mfma_f32_16x16x32_bf16 v[106:109], v[182:185], v[206:209], v[106:109]
	v_mfma_f32_16x16x32_bf16 v[94:97], v[160:163], v[214:217], v[94:97]
	v_mfma_f32_16x16x32_bf16 v[90:93], v[182:185], v[214:217], v[90:93]
	v_mfma_f32_16x16x32_bf16 v[78:81], v[160:163], v[222:225], v[78:81]
	v_mfma_f32_16x16x32_bf16 v[74:77], v[182:185], v[222:225], v[74:77]
	v_mfma_f32_16x16x32_bf16 v[70:73], v[160:163], v[230:233], v[70:73]
	v_mfma_f32_16x16x32_bf16 v[66:69], v[182:185], v[230:233], v[66:69]
	v_mfma_f32_16x16x32_bf16 v[110:113], v[178:181], v[210:213], v[110:113]
	v_mfma_f32_16x16x32_bf16 v[106:109], v[186:189], v[210:213], v[106:109]
	v_mfma_f32_16x16x32_bf16 v[94:97], v[178:181], v[218:221], v[94:97]
	v_mfma_f32_16x16x32_bf16 v[90:93], v[186:189], v[218:221], v[90:93]
	v_mfma_f32_16x16x32_bf16 v[78:81], v[178:181], v[226:229], v[78:81]
	v_mfma_f32_16x16x32_bf16 v[74:77], v[186:189], v[226:229], v[74:77]
	v_mfma_f32_16x16x32_bf16 v[70:73], v[178:181], v[234:237], v[70:73]
	v_mfma_f32_16x16x32_bf16 v[66:69], v[186:189], v[234:237], v[66:69]
	s_barrier
	s_setprio 0
	s_add_i32 s46, s62, s72
	v_lshl_add_u64 v[164:165], v[164:165], 0, s[42:43]
	s_mov_b32 m0, s46
	ds_read_b128 v[206:209], v142 offset:49152
	ds_read_b128 v[210:213], v142 offset:50176
	ds_read_b128 v[214:217], v142 offset:51200
	ds_read_b128 v[218:221], v142 offset:52224
	ds_read_b128 v[222:225], v142 offset:53248
	ds_read_b128 v[226:229], v142 offset:54272
	ds_read_b128 v[230:233], v142 offset:55296
	ds_read_b128 v[234:237], v142 offset:56320
	global_load_lds_dwordx4 v[164:165], off
	s_add_i32 m0, s46, 0x2000
	s_add_u32 s46, s60, 0x20080
	v_lshl_add_u64 v[164:165], v[242:243], 0, s[42:43]
	s_addc_u32 s47, s61, 0
	s_add_i32 s60, s63, s72
	global_load_lds_dwordx4 v[164:165], off
	v_lshl_add_u64 v[164:165], s[46:47], 0, v[166:167]
	s_mov_b32 m0, s60
	s_nop 0
	global_load_lds_dwordx4 v[164:165], off
	v_lshl_add_u64 v[164:165], s[46:47], 0, v[130:131]
	s_add_i32 m0, s60, 0x2000
	s_nop 0
	global_load_lds_dwordx4 v[164:165], off
	v_lshl_add_u64 v[164:165], v[244:245], 0, s[42:43]
	s_mov_b32 m0, s77
	s_nop 0
	global_load_lds_dwordx4 v[164:165], off
	v_lshl_add_u64 v[164:165], v[246:247], 0, s[42:43]
	s_mov_b32 m0, s78
	s_nop 0
	global_load_lds_dwordx4 v[164:165], off
	s_waitcnt vmcnt(8)
	s_waitcnt lgkmcnt(0)
	s_setprio 1
	s_waitcnt lgkmcnt(0)
	v_mfma_f32_16x16x32_bf16 v[62:65], v[144:147], v[206:209], v[62:65]
	v_mfma_f32_16x16x32_bf16 v[58:61], v[152:155], v[206:209], v[58:61]
	v_mfma_f32_16x16x32_bf16 v[54:57], v[144:147], v[214:217], v[54:57]
	v_mfma_f32_16x16x32_bf16 v[50:53], v[152:155], v[214:217], v[50:53]
	v_mfma_f32_16x16x32_bf16 v[38:41], v[144:147], v[222:225], v[38:41]
	v_mfma_f32_16x16x32_bf16 v[34:37], v[152:155], v[222:225], v[34:37]
	s_barrier
	v_mfma_f32_16x16x32_bf16 v[22:25], v[144:147], v[230:233], v[22:25]
	v_mfma_f32_16x16x32_bf16 v[18:21], v[152:155], v[230:233], v[18:21]
	v_mfma_f32_16x16x32_bf16 v[62:65], v[148:151], v[210:213], v[62:65]
	v_mfma_f32_16x16x32_bf16 v[58:61], v[156:159], v[210:213], v[58:61]
	v_mfma_f32_16x16x32_bf16 v[54:57], v[148:151], v[218:221], v[54:57]
	v_mfma_f32_16x16x32_bf16 v[50:53], v[156:159], v[218:221], v[50:53]
	v_mfma_f32_16x16x32_bf16 v[38:41], v[148:151], v[226:229], v[38:41]
	v_mfma_f32_16x16x32_bf16 v[34:37], v[156:159], v[226:229], v[34:37]
	v_mfma_f32_16x16x32_bf16 v[22:25], v[148:151], v[234:237], v[22:25]
	v_mfma_f32_16x16x32_bf16 v[18:21], v[156:159], v[234:237], v[18:21]
	v_mfma_f32_16x16x32_bf16 v[46:49], v[160:163], v[206:209], v[46:49]
	v_mfma_f32_16x16x32_bf16 v[42:45], v[182:185], v[206:209], v[42:45]
	v_mfma_f32_16x16x32_bf16 v[30:33], v[160:163], v[214:217], v[30:33]
	v_mfma_f32_16x16x32_bf16 v[26:29], v[182:185], v[214:217], v[26:29]
	v_mfma_f32_16x16x32_bf16 v[14:17], v[160:163], v[222:225], v[14:17]
	v_mfma_f32_16x16x32_bf16 v[10:13], v[182:185], v[222:225], v[10:13]
	v_mfma_f32_16x16x32_bf16 v[6:9], v[160:163], v[230:233], v[6:9]
	v_mfma_f32_16x16x32_bf16 v[2:5], v[182:185], v[230:233], v[2:5]
	v_mfma_f32_16x16x32_bf16 v[46:49], v[178:181], v[210:213], v[46:49]
	v_mfma_f32_16x16x32_bf16 v[42:45], v[186:189], v[210:213], v[42:45]
	v_mfma_f32_16x16x32_bf16 v[30:33], v[178:181], v[218:221], v[30:33]
	v_mfma_f32_16x16x32_bf16 v[26:29], v[186:189], v[218:221], v[26:29]
	v_mfma_f32_16x16x32_bf16 v[14:17], v[178:181], v[226:229], v[14:17]
	v_mfma_f32_16x16x32_bf16 v[10:13], v[186:189], v[226:229], v[10:13]
	v_mfma_f32_16x16x32_bf16 v[6:9], v[178:181], v[234:237], v[6:9]
	v_mfma_f32_16x16x32_bf16 v[2:5], v[186:189], v[234:237], v[2:5]
	s_barrier
	s_setprio 0
	s_add_i32 s84, s84, 2
	s_add_u32 s66, s66, 0x100
	s_addc_u32 s67, s67, 0
	s_add_u32 s82, s82, 0x100
	s_addc_u32 s83, s83, 0
	s_cmp_gt_u32 s84, 5
	s_cbranch_scc0 .LBB0_426
	s_and_b64 vcc, exec, s[12:13]
	s_cbranch_vccz .LBB0_429
	s_barrier

.LBB0_442:
	s_add_u32 s62, s18, s72
	s_addc_u32 s63, s19, 0
	s_add_u32 s73, s62, 0x100
	s_addc_u32 s74, s63, 0
	s_and_b64 s[46:47], s[60:61], exec
	s_cselect_b32 s75, s23, s74
	s_cselect_b32 s74, s92, s73
	s_add_u32 s46, s16, s72
	s_addc_u32 s47, s17, 0
	s_add_u32 s72, s46, 0x100
	s_addc_u32 s73, s47, 0
	s_add_i32 s48, 0, 0x10000
	s_and_b64 s[46:47], s[60:61], exec
	s_cselect_b32 s77, s21, s73
	s_cselect_b32 s76, s93, s72
	s_add_i32 s46, 0, 0x14000
	s_add_u32 s80, s62, 0x10080
	s_addc_u32 s81, s63, 0
	s_add_i32 s63, s48, s84
	s_add_i32 m0, s13, 0xc000
	s_add_i32 s49, s13, 0xe000
	s_add_i32 vcc_lo, s63, 0x2000
	v_add_u32_e32 v139, s48, v136
	s_add_u32 s78, s76, 0x10000
	ds_read_b128 v[140:143], v139
	ds_read_b128 v[144:147], v139 offset:1024
	ds_read_b128 v[148:151], v139 offset:2048
	ds_read_b128 v[152:155], v139 offset:3072
	v_add_u32_e32 v139, s46, v136
	s_addc_u32 s79, s77, 0
	s_add_i32 vcc_hi, s46, s84
	ds_read_b128 v[156:159], v139
	ds_read_b128 v[160:163], v139 offset:1024
	ds_read_b128 v[178:181], v139 offset:2048
	ds_read_b128 v[182:185], v139 offset:3072
	s_add_i32 s62, vcc_hi, 0x2000
	s_add_i32 s97, 0, 0x18000
	s_add_i32 s96, 0, 0x1c000
	s_add_u32 s72, s74, 0x10000
	s_addc_u32 s73, s75, 0
	s_add_i32 s95, s97, s84
	s_add_i32 s94, s95, 0x2000
	s_add_u32 s60, s76, 0x10080
	s_addc_u32 s61, s77, 0
	s_add_i32 s47, s96, s84
	s_add_i32 s46, s47, 0x2000
	v_lshl_add_u64 v[164:165], s[80:81], 0, v[134:135]
	ds_read_b128 v[186:189], v138
	ds_read_b128 v[206:209], v138 offset:1024
	ds_read_b128 v[210:213], v138 offset:2048
	ds_read_b128 v[214:217], v138 offset:3072
	ds_read_b128 v[218:221], v138 offset:4096
	ds_read_b128 v[222:225], v138 offset:5120
	ds_read_b128 v[226:229], v138 offset:6144
	ds_read_b128 v[230:233], v138 offset:7168
	global_load_lds_dwordx4 v[164:165], off
	v_lshl_add_u64 v[164:165], s[80:81], 0, v[132:133]
	s_mov_b32 m0, s49
	s_nop 0
	global_load_lds_dwordx4 v[164:165], off
	s_waitcnt vmcnt(8)
	s_waitcnt lgkmcnt(0)
	s_setprio 1
	s_waitcnt lgkmcnt(0)
	v_mfma_f32_16x16x32_bf16 v[126:129], v[140:143], v[186:189], v[126:129]
	v_mfma_f32_16x16x32_bf16 v[122:125], v[148:151], v[186:189], v[122:125]
	v_mfma_f32_16x16x32_bf16 v[118:121], v[140:143], v[210:213], v[118:121]
	v_mfma_f32_16x16x32_bf16 v[114:117], v[148:151], v[210:213], v[114:117]
	v_mfma_f32_16x16x32_bf16 v[102:105], v[140:143], v[218:221], v[102:105]
	v_mfma_f32_16x16x32_bf16 v[98:101], v[148:151], v[218:221], v[98:101]
	s_barrier
	v_mfma_f32_16x16x32_bf16 v[86:89], v[140:143], v[226:229], v[86:89]
	v_mfma_f32_16x16x32_bf16 v[82:85], v[148:151], v[226:229], v[82:85]
	v_mfma_f32_16x16x32_bf16 v[126:129], v[144:147], v[206:209], v[126:129]
	v_mfma_f32_16x16x32_bf16 v[122:125], v[152:155], v[206:209], v[122:125]
	v_mfma_f32_16x16x32_bf16 v[118:121], v[144:147], v[214:217], v[118:121]
	v_mfma_f32_16x16x32_bf16 v[114:117], v[152:155], v[214:217], v[114:117]
	v_mfma_f32_16x16x32_bf16 v[102:105], v[144:147], v[222:225], v[102:105]
	v_mfma_f32_16x16x32_bf16 v[98:101], v[152:155], v[222:225], v[98:101]
	v_mfma_f32_16x16x32_bf16 v[86:89], v[144:147], v[230:233], v[86:89]
	v_mfma_f32_16x16x32_bf16 v[82:85], v[152:155], v[230:233], v[82:85]
	v_mfma_f32_16x16x32_bf16 v[110:113], v[156:159], v[186:189], v[110:113]
	v_mfma_f32_16x16x32_bf16 v[106:109], v[178:181], v[186:189], v[106:109]
	v_mfma_f32_16x16x32_bf16 v[94:97], v[156:159], v[210:213], v[94:97]
	v_mfma_f32_16x16x32_bf16 v[90:93], v[178:181], v[210:213], v[90:93]
	v_mfma_f32_16x16x32_bf16 v[78:81], v[156:159], v[218:221], v[78:81]
	v_mfma_f32_16x16x32_bf16 v[74:77], v[178:181], v[218:221], v[74:77]
	v_mfma_f32_16x16x32_bf16 v[70:73], v[156:159], v[226:229], v[70:73]
	v_mfma_f32_16x16x32_bf16 v[66:69], v[178:181], v[226:229], v[66:69]
	v_mfma_f32_16x16x32_bf16 v[110:113], v[160:163], v[206:209], v[110:113]
	v_mfma_f32_16x16x32_bf16 v[106:109], v[182:185], v[206:209], v[106:109]
	v_mfma_f32_16x16x32_bf16 v[94:97], v[160:163], v[214:217], v[94:97]
	v_mfma_f32_16x16x32_bf16 v[90:93], v[182:185], v[214:217], v[90:93]
	v_mfma_f32_16x16x32_bf16 v[78:81], v[160:163], v[222:225], v[78:81]
	v_mfma_f32_16x16x32_bf16 v[74:77], v[182:185], v[222:225], v[74:77]
	v_mfma_f32_16x16x32_bf16 v[70:73], v[160:163], v[230:233], v[70:73]
	v_mfma_f32_16x16x32_bf16 v[66:69], v[182:185], v[230:233], v[66:69]
	s_barrier
	s_setprio 0
	s_mov_b32 m0, s63
	v_lshl_add_u64 v[164:165], s[76:77], 0, v[166:167]
	ds_read_b128 v[186:189], v138 offset:16384
	ds_read_b128 v[206:209], v138 offset:17408
	ds_read_b128 v[210:213], v138 offset:18432
	ds_read_b128 v[214:217], v138 offset:19456
	ds_read_b128 v[218:221], v138 offset:20480
	ds_read_b128 v[222:225], v138 offset:21504
	ds_read_b128 v[226:229], v138 offset:22528
	ds_read_b128 v[230:233], v138 offset:23552
	global_load_lds_dwordx4 v[164:165], off
	v_lshl_add_u64 v[234:235], s[76:77], 0, v[130:131]
	s_mov_b32 m0, vcc_lo
	v_lshl_add_u64 v[236:237], s[78:79], 0, v[166:167]
	global_load_lds_dwordx4 v[234:235], off
	s_mov_b32 m0, vcc_hi
	v_lshl_add_u64 v[242:243], s[74:75], 0, v[132:133]
	global_load_lds_dwordx4 v[236:237], off
	v_lshl_add_u64 v[236:237], s[78:79], 0, v[130:131]
	s_mov_b32 m0, s62
	s_nop 0
	global_load_lds_dwordx4 v[236:237], off
	v_lshl_add_u64 v[236:237], s[74:75], 0, v[134:135]
	s_mov_b32 m0, s13
	s_nop 0
	global_load_lds_dwordx4 v[236:237], off
	s_mov_b32 m0, s86
	s_nop 0
	global_load_lds_dwordx4 v[242:243], off
	s_waitcnt vmcnt(8)
	s_waitcnt lgkmcnt(0)
	s_setprio 1
	s_waitcnt lgkmcnt(0)
	v_mfma_f32_16x16x32_bf16 v[62:65], v[140:143], v[186:189], v[62:65]
	v_mfma_f32_16x16x32_bf16 v[58:61], v[148:151], v[186:189], v[58:61]
	v_mfma_f32_16x16x32_bf16 v[54:57], v[140:143], v[210:213], v[54:57]
	v_mfma_f32_16x16x32_bf16 v[50:53], v[148:151], v[210:213], v[50:53]
	v_mfma_f32_16x16x32_bf16 v[38:41], v[140:143], v[218:221], v[38:41]
	v_mfma_f32_16x16x32_bf16 v[34:37], v[148:151], v[218:221], v[34:37]
	s_barrier
	v_mfma_f32_16x16x32_bf16 v[22:25], v[140:143], v[226:229], v[22:25]
	v_mfma_f32_16x16x32_bf16 v[18:21], v[148:151], v[226:229], v[18:21]
	v_mfma_f32_16x16x32_bf16 v[62:65], v[144:147], v[206:209], v[62:65]
	v_mfma_f32_16x16x32_bf16 v[58:61], v[152:155], v[206:209], v[58:61]
	v_mfma_f32_16x16x32_bf16 v[54:57], v[144:147], v[214:217], v[54:57]
	v_mfma_f32_16x16x32_bf16 v[50:53], v[152:155], v[214:217], v[50:53]
	v_mfma_f32_16x16x32_bf16 v[38:41], v[144:147], v[222:225], v[38:41]
	v_mfma_f32_16x16x32_bf16 v[34:37], v[152:155], v[222:225], v[34:37]
	v_mfma_f32_16x16x32_bf16 v[22:25], v[144:147], v[230:233], v[22:25]
	v_mfma_f32_16x16x32_bf16 v[18:21], v[152:155], v[230:233], v[18:21]
	v_mfma_f32_16x16x32_bf16 v[46:49], v[156:159], v[186:189], v[46:49]
	v_mfma_f32_16x16x32_bf16 v[42:45], v[178:181], v[186:189], v[42:45]
	v_mfma_f32_16x16x32_bf16 v[30:33], v[156:159], v[210:213], v[30:33]
	v_mfma_f32_16x16x32_bf16 v[26:29], v[178:181], v[210:213], v[26:29]
	v_mfma_f32_16x16x32_bf16 v[14:17], v[156:159], v[218:221], v[14:17]
	v_mfma_f32_16x16x32_bf16 v[10:13], v[178:181], v[218:221], v[10:13]
	v_mfma_f32_16x16x32_bf16 v[6:9], v[156:159], v[226:229], v[6:9]
	v_mfma_f32_16x16x32_bf16 v[2:5], v[178:181], v[226:229], v[2:5]
	v_mfma_f32_16x16x32_bf16 v[46:49], v[160:163], v[206:209], v[46:49]
	v_mfma_f32_16x16x32_bf16 v[42:45], v[182:185], v[206:209], v[42:45]
	v_mfma_f32_16x16x32_bf16 v[30:33], v[160:163], v[214:217], v[30:33]
	v_mfma_f32_16x16x32_bf16 v[26:29], v[182:185], v[214:217], v[26:29]
	v_mfma_f32_16x16x32_bf16 v[14:17], v[160:163], v[222:225], v[14:17]
	v_mfma_f32_16x16x32_bf16 v[10:13], v[182:185], v[222:225], v[10:13]
	v_mfma_f32_16x16x32_bf16 v[6:9], v[160:163], v[230:233], v[6:9]
	v_mfma_f32_16x16x32_bf16 v[2:5], v[182:185], v[230:233], v[2:5]
	s_barrier
	s_setprio 0
	v_add_u32_e32 v139, s97, v136
	ds_read_b128 v[140:143], v139
	ds_read_b128 v[144:147], v139 offset:1024
	ds_read_b128 v[148:151], v139 offset:2048
	ds_read_b128 v[152:155], v139 offset:3072
	v_add_u32_e32 v139, s96, v136
	ds_read_b128 v[156:159], v139
	ds_read_b128 v[160:163], v139 offset:1024
	ds_read_b128 v[178:181], v139 offset:2048
	ds_read_b128 v[182:185], v139 offset:3072
	s_mov_b32 m0, s87
	v_lshl_add_u64 v[244:245], s[72:73], 0, v[134:135]
	ds_read_b128 v[186:189], v138 offset:32768
	ds_read_b128 v[206:209], v138 offset:33792
	ds_read_b128 v[210:213], v138 offset:34816
	ds_read_b128 v[214:217], v138 offset:35840
	ds_read_b128 v[218:221], v138 offset:36864
	ds_read_b128 v[222:225], v138 offset:37888
	ds_read_b128 v[226:229], v138 offset:38912
	ds_read_b128 v[230:233], v138 offset:39936
	global_load_lds_dwordx4 v[244:245], off
	v_lshl_add_u64 v[244:245], s[72:73], 0, v[132:133]
	s_mov_b32 m0, s88
	s_nop 0
	global_load_lds_dwordx4 v[244:245], off
	s_waitcnt vmcnt(8)
	s_waitcnt lgkmcnt(0)
	s_setprio 1
	s_waitcnt lgkmcnt(0)
	v_mfma_f32_16x16x32_bf16 v[126:129], v[140:143], v[186:189], v[126:129]
	v_mfma_f32_16x16x32_bf16 v[122:125], v[148:151], v[186:189], v[122:125]
	v_mfma_f32_16x16x32_bf16 v[118:121], v[140:143], v[210:213], v[118:121]
	v_mfma_f32_16x16x32_bf16 v[114:117], v[148:151], v[210:213], v[114:117]
	v_mfma_f32_16x16x32_bf16 v[102:105], v[140:143], v[218:221], v[102:105]
	v_mfma_f32_16x16x32_bf16 v[98:101], v[148:151], v[218:221], v[98:101]
	s_barrier
	v_mfma_f32_16x16x32_bf16 v[86:89], v[140:143], v[226:229], v[86:89]
	v_mfma_f32_16x16x32_bf16 v[82:85], v[148:151], v[226:229], v[82:85]
	v_mfma_f32_16x16x32_bf16 v[126:129], v[144:147], v[206:209], v[126:129]
	v_mfma_f32_16x16x32_bf16 v[122:125], v[152:155], v[206:209], v[122:125]
	v_mfma_f32_16x16x32_bf16 v[118:121], v[144:147], v[214:217], v[118:121]
	v_mfma_f32_16x16x32_bf16 v[114:117], v[152:155], v[214:217], v[114:117]
	v_mfma_f32_16x16x32_bf16 v[102:105], v[144:147], v[222:225], v[102:105]
	v_mfma_f32_16x16x32_bf16 v[98:101], v[152:155], v[222:225], v[98:101]
	v_mfma_f32_16x16x32_bf16 v[86:89], v[144:147], v[230:233], v[86:89]
	v_mfma_f32_16x16x32_bf16 v[82:85], v[152:155], v[230:233], v[82:85]
	v_mfma_f32_16x16x32_bf16 v[110:113], v[156:159], v[186:189], v[110:113]
	v_mfma_f32_16x16x32_bf16 v[106:109], v[178:181], v[186:189], v[106:109]
	v_mfma_f32_16x16x32_bf16 v[94:97], v[156:159], v[210:213], v[94:97]
	v_mfma_f32_16x16x32_bf16 v[90:93], v[178:181], v[210:213], v[90:93]
	v_mfma_f32_16x16x32_bf16 v[78:81], v[156:159], v[218:221], v[78:81]
	v_mfma_f32_16x16x32_bf16 v[74:77], v[178:181], v[218:221], v[74:77]
	v_mfma_f32_16x16x32_bf16 v[70:73], v[156:159], v[226:229], v[70:73]
	v_mfma_f32_16x16x32_bf16 v[66:69], v[178:181], v[226:229], v[66:69]
	v_mfma_f32_16x16x32_bf16 v[110:113], v[160:163], v[206:209], v[110:113]
	v_mfma_f32_16x16x32_bf16 v[106:109], v[182:185], v[206:209], v[106:109]
	v_mfma_f32_16x16x32_bf16 v[94:97], v[160:163], v[214:217], v[94:97]
	v_mfma_f32_16x16x32_bf16 v[90:93], v[182:185], v[214:217], v[90:93]
	v_mfma_f32_16x16x32_bf16 v[78:81], v[160:163], v[222:225], v[78:81]
	v_mfma_f32_16x16x32_bf16 v[74:77], v[182:185], v[222:225], v[74:77]
	v_mfma_f32_16x16x32_bf16 v[70:73], v[160:163], v[230:233], v[70:73]
	v_mfma_f32_16x16x32_bf16 v[66:69], v[182:185], v[230:233], v[66:69]
	s_barrier
	s_setprio 0
	s_mov_b32 m0, s95
	v_lshl_add_u64 v[164:165], v[164:165], 0, s[42:43]
	ds_read_b128 v[186:189], v138 offset:49152
	ds_read_b128 v[206:209], v138 offset:50176
	ds_read_b128 v[210:213], v138 offset:51200
	ds_read_b128 v[214:217], v138 offset:52224
	ds_read_b128 v[218:221], v138 offset:53248
	ds_read_b128 v[222:225], v138 offset:54272
	ds_read_b128 v[226:229], v138 offset:55296
	ds_read_b128 v[230:233], v138 offset:56320
	global_load_lds_dwordx4 v[164:165], off
	v_lshl_add_u64 v[164:165], v[234:235], 0, s[42:43]
	s_mov_b32 m0, s94
	s_nop 0
	global_load_lds_dwordx4 v[164:165], off
	v_lshl_add_u64 v[164:165], s[60:61], 0, v[166:167]
	s_mov_b32 m0, s47
	s_nop 0
	global_load_lds_dwordx4 v[164:165], off
	v_lshl_add_u64 v[164:165], s[60:61], 0, v[130:131]
	s_mov_b32 m0, s46
	s_nop 0
	global_load_lds_dwordx4 v[164:165], off
	v_lshl_add_u64 v[164:165], v[236:237], 0, s[42:43]
	s_mov_b32 m0, s89
	s_nop 0
	global_load_lds_dwordx4 v[164:165], off
	v_lshl_add_u64 v[164:165], v[242:243], 0, s[42:43]
	s_mov_b32 m0, s90
	s_nop 0
	global_load_lds_dwordx4 v[164:165], off
	s_waitcnt vmcnt(8)
	s_waitcnt lgkmcnt(0)
	s_setprio 1
	s_waitcnt lgkmcnt(0)
	v_mfma_f32_16x16x32_bf16 v[62:65], v[140:143], v[186:189], v[62:65]
	v_mfma_f32_16x16x32_bf16 v[58:61], v[148:151], v[186:189], v[58:61]
	v_mfma_f32_16x16x32_bf16 v[54:57], v[140:143], v[210:213], v[54:57]
	v_mfma_f32_16x16x32_bf16 v[50:53], v[148:151], v[210:213], v[50:53]
	v_mfma_f32_16x16x32_bf16 v[38:41], v[140:143], v[218:221], v[38:41]
	v_mfma_f32_16x16x32_bf16 v[34:37], v[148:151], v[218:221], v[34:37]
	s_barrier
	v_mfma_f32_16x16x32_bf16 v[22:25], v[140:143], v[226:229], v[22:25]
	v_mfma_f32_16x16x32_bf16 v[18:21], v[148:151], v[226:229], v[18:21]
	v_mfma_f32_16x16x32_bf16 v[62:65], v[144:147], v[206:209], v[62:65]
	v_mfma_f32_16x16x32_bf16 v[58:61], v[152:155], v[206:209], v[58:61]
	v_mfma_f32_16x16x32_bf16 v[54:57], v[144:147], v[214:217], v[54:57]
	v_mfma_f32_16x16x32_bf16 v[50:53], v[152:155], v[214:217], v[50:53]
	v_mfma_f32_16x16x32_bf16 v[38:41], v[144:147], v[222:225], v[38:41]
	v_mfma_f32_16x16x32_bf16 v[34:37], v[152:155], v[222:225], v[34:37]
	v_mfma_f32_16x16x32_bf16 v[22:25], v[144:147], v[230:233], v[22:25]
	v_mfma_f32_16x16x32_bf16 v[18:21], v[152:155], v[230:233], v[18:21]
	v_mfma_f32_16x16x32_bf16 v[46:49], v[156:159], v[186:189], v[46:49]
	v_mfma_f32_16x16x32_bf16 v[42:45], v[178:181], v[186:189], v[42:45]
	v_mfma_f32_16x16x32_bf16 v[30:33], v[156:159], v[210:213], v[30:33]
	v_mfma_f32_16x16x32_bf16 v[26:29], v[178:181], v[210:213], v[26:29]
	v_mfma_f32_16x16x32_bf16 v[14:17], v[156:159], v[218:221], v[14:17]
	v_mfma_f32_16x16x32_bf16 v[10:13], v[178:181], v[218:221], v[10:13]
	v_mfma_f32_16x16x32_bf16 v[6:9], v[156:159], v[226:229], v[6:9]
	v_mfma_f32_16x16x32_bf16 v[2:5], v[178:181], v[226:229], v[2:5]
	v_mfma_f32_16x16x32_bf16 v[46:49], v[160:163], v[206:209], v[46:49]
	v_mfma_f32_16x16x32_bf16 v[42:45], v[182:185], v[206:209], v[42:45]
	v_mfma_f32_16x16x32_bf16 v[30:33], v[160:163], v[214:217], v[30:33]
	v_mfma_f32_16x16x32_bf16 v[26:29], v[182:185], v[214:217], v[26:29]
	v_mfma_f32_16x16x32_bf16 v[14:17], v[160:163], v[222:225], v[14:17]
	v_mfma_f32_16x16x32_bf16 v[10:13], v[182:185], v[222:225], v[10:13]
	v_mfma_f32_16x16x32_bf16 v[6:9], v[160:163], v[230:233], v[6:9]
	v_mfma_f32_16x16x32_bf16 v[2:5], v[182:185], v[230:233], v[2:5]
	s_barrier
	s_setprio 0
	s_movk_i32 s72, 0x100
	s_andn2_b64 vcc, exec, s[70:71]
	s_mov_b64 s[60:61], -1
	s_mov_b64 s[70:71], 0
	s_cbranch_vccz .LBB0_442
	s_and_b64 vcc, exec, s[10:11]
	s_cbranch_vccz .LBB0_445
	s_barrier

.LBB0_795:
	s_add_u32 s46, s68, 0xfff80080
	s_addc_u32 s47, s69, -1
	s_add_i32 s48, 0, 0x10000
	s_cmp_eq_u32 s87, 28
	s_cselect_b32 s71, s19, s47
	s_cselect_b32 s70, s83, s46
	s_cselect_b32 s61, s17, s86
	s_cselect_b32 s60, s84, s85
	s_add_i32 s49, 0, 0x14000
	v_add_u32_e32 v156, s48, v1
	v_add_u32_e32 v164, s49, v1
	ds_read_b128 v[130:133], v156
	ds_read_b128 v[134:137], v156 offset:1024
	ds_read_b128 v[150:153], v156 offset:2048
	ds_read_b128 v[156:159], v156 offset:3072
	ds_read_b128 v[160:163], v164
	ds_read_b128 v[178:181], v164 offset:1024
	ds_read_b128 v[182:185], v164 offset:2048
	ds_read_b128 v[186:189], v164 offset:3072
	v_lshl_add_u64 v[164:165], s[68:69], 0, v[146:147]
	s_add_i32 m0, s67, 0xc000
	ds_read_b128 v[206:209], v155
	ds_read_b128 v[210:213], v155 offset:1024
	ds_read_b128 v[214:217], v155 offset:2048
	ds_read_b128 v[218:221], v155 offset:3072
	ds_read_b128 v[222:225], v155 offset:4096
	ds_read_b128 v[226:229], v155 offset:5120
	ds_read_b128 v[230:233], v155 offset:6144
	ds_read_b128 v[234:237], v155 offset:7168
	global_load_lds_dwordx4 v[164:165], off
	v_lshl_add_u64 v[164:165], s[68:69], 0, v[148:149]
	s_add_i32 m0, s67, 0xe000
	s_nop 0
	global_load_lds_dwordx4 v[164:165], off
	s_waitcnt vmcnt(8)
	s_waitcnt lgkmcnt(0)
	s_setprio 1
	s_waitcnt lgkmcnt(0)
	v_mfma_f32_16x16x32_bf16 v[126:129], v[130:133], v[206:209], v[126:129]
	v_mfma_f32_16x16x32_bf16 v[122:125], v[150:153], v[206:209], v[122:125]
	v_mfma_f32_16x16x32_bf16 v[118:121], v[130:133], v[214:217], v[118:121]
	v_mfma_f32_16x16x32_bf16 v[114:117], v[150:153], v[214:217], v[114:117]
	v_mfma_f32_16x16x32_bf16 v[110:113], v[130:133], v[222:225], v[110:113]
	v_mfma_f32_16x16x32_bf16 v[106:109], v[150:153], v[222:225], v[106:109]
	s_barrier
	v_mfma_f32_16x16x32_bf16 v[102:105], v[130:133], v[230:233], v[102:105]
	v_mfma_f32_16x16x32_bf16 v[98:101], v[150:153], v[230:233], v[98:101]
	v_mfma_f32_16x16x32_bf16 v[126:129], v[134:137], v[210:213], v[126:129]
	v_mfma_f32_16x16x32_bf16 v[122:125], v[156:159], v[210:213], v[122:125]
	v_mfma_f32_16x16x32_bf16 v[118:121], v[134:137], v[218:221], v[118:121]
	v_mfma_f32_16x16x32_bf16 v[114:117], v[156:159], v[218:221], v[114:117]
	v_mfma_f32_16x16x32_bf16 v[110:113], v[134:137], v[226:229], v[110:113]
	v_mfma_f32_16x16x32_bf16 v[106:109], v[156:159], v[226:229], v[106:109]
	v_mfma_f32_16x16x32_bf16 v[102:105], v[134:137], v[234:237], v[102:105]
	v_mfma_f32_16x16x32_bf16 v[98:101], v[156:159], v[234:237], v[98:101]
	v_mfma_f32_16x16x32_bf16 v[66:69], v[160:163], v[206:209], v[66:69]
	v_mfma_f32_16x16x32_bf16 v[58:61], v[182:185], v[206:209], v[58:61]
	v_mfma_f32_16x16x32_bf16 v[54:57], v[160:163], v[214:217], v[54:57]
	v_mfma_f32_16x16x32_bf16 v[50:53], v[182:185], v[214:217], v[50:53]
	v_mfma_f32_16x16x32_bf16 v[46:49], v[160:163], v[222:225], v[46:49]
	v_mfma_f32_16x16x32_bf16 v[42:45], v[182:185], v[222:225], v[42:45]
	v_mfma_f32_16x16x32_bf16 v[38:41], v[160:163], v[230:233], v[38:41]
	v_mfma_f32_16x16x32_bf16 v[34:37], v[182:185], v[230:233], v[34:37]
	v_mfma_f32_16x16x32_bf16 v[66:69], v[178:181], v[210:213], v[66:69]
	v_mfma_f32_16x16x32_bf16 v[58:61], v[186:189], v[210:213], v[58:61]
	v_mfma_f32_16x16x32_bf16 v[54:57], v[178:181], v[218:221], v[54:57]
	v_mfma_f32_16x16x32_bf16 v[50:53], v[186:189], v[218:221], v[50:53]
	v_mfma_f32_16x16x32_bf16 v[46:49], v[178:181], v[226:229], v[46:49]
	v_mfma_f32_16x16x32_bf16 v[42:45], v[186:189], v[226:229], v[42:45]
	v_mfma_f32_16x16x32_bf16 v[38:41], v[178:181], v[234:237], v[38:41]
	v_mfma_f32_16x16x32_bf16 v[34:37], v[186:189], v[234:237], v[34:37]
	s_barrier
	s_setprio 0
	s_add_i32 s46, s48, s77
	v_lshl_add_u64 v[164:165], s[60:61], 0, v[166:167]
	s_mov_b32 m0, s46
	ds_read_b128 v[206:209], v155 offset:16384
	ds_read_b128 v[210:213], v155 offset:17408
	ds_read_b128 v[214:217], v155 offset:18432
	ds_read_b128 v[218:221], v155 offset:19456
	ds_read_b128 v[222:225], v155 offset:20480
	ds_read_b128 v[226:229], v155 offset:21504
	ds_read_b128 v[230:233], v155 offset:22528
	ds_read_b128 v[234:237], v155 offset:23552
	global_load_lds_dwordx4 v[164:165], off
	s_add_i32 m0, s46, 0x2000
	s_add_u32 s46, s60, 0x80000
	v_lshl_add_u64 v[242:243], s[60:61], 0, v[142:143]
	s_addc_u32 s47, s61, 0
	s_add_i32 s48, s49, s77
	global_load_lds_dwordx4 v[242:243], off
	v_lshl_add_u64 v[244:245], s[46:47], 0, v[166:167]
	s_mov_b32 m0, s48
	v_lshl_add_u64 v[246:247], s[70:71], 0, v[140:141]
	global_load_lds_dwordx4 v[244:245], off
	v_lshl_add_u64 v[244:245], s[46:47], 0, v[142:143]
	s_add_i32 m0, s48, 0x2000
	s_nop 0
	global_load_lds_dwordx4 v[244:245], off
	v_lshl_add_u64 v[244:245], s[70:71], 0, v[138:139]
	s_mov_b32 m0, s67
	s_nop 0
	global_load_lds_dwordx4 v[244:245], off
	s_mov_b32 m0, s78
	s_nop 0
	global_load_lds_dwordx4 v[246:247], off
	s_waitcnt vmcnt(8)
	s_waitcnt lgkmcnt(0)
	s_setprio 1
	s_waitcnt lgkmcnt(0)
	v_mfma_f32_16x16x32_bf16 v[94:97], v[130:133], v[206:209], v[94:97]
	v_mfma_f32_16x16x32_bf16 v[90:93], v[150:153], v[206:209], v[90:93]
	v_mfma_f32_16x16x32_bf16 v[86:89], v[130:133], v[214:217], v[86:89]
	v_mfma_f32_16x16x32_bf16 v[82:85], v[150:153], v[214:217], v[82:85]
	v_mfma_f32_16x16x32_bf16 v[78:81], v[130:133], v[222:225], v[78:81]
	v_mfma_f32_16x16x32_bf16 v[74:77], v[150:153], v[222:225], v[74:77]
	s_barrier
	v_mfma_f32_16x16x32_bf16 v[70:73], v[130:133], v[230:233], v[70:73]
	v_mfma_f32_16x16x32_bf16 v[62:65], v[150:153], v[230:233], v[62:65]
	v_mfma_f32_16x16x32_bf16 v[94:97], v[134:137], v[210:213], v[94:97]
	v_mfma_f32_16x16x32_bf16 v[90:93], v[156:159], v[210:213], v[90:93]
	v_mfma_f32_16x16x32_bf16 v[86:89], v[134:137], v[218:221], v[86:89]
	v_mfma_f32_16x16x32_bf16 v[82:85], v[156:159], v[218:221], v[82:85]
	v_mfma_f32_16x16x32_bf16 v[78:81], v[134:137], v[226:229], v[78:81]
	v_mfma_f32_16x16x32_bf16 v[74:77], v[156:159], v[226:229], v[74:77]
	v_mfma_f32_16x16x32_bf16 v[70:73], v[134:137], v[234:237], v[70:73]
	v_mfma_f32_16x16x32_bf16 v[62:65], v[156:159], v[234:237], v[62:65]
	v_mfma_f32_16x16x32_bf16 v[30:33], v[160:163], v[206:209], v[30:33]
	v_mfma_f32_16x16x32_bf16 v[26:29], v[182:185], v[206:209], v[26:29]
	v_mfma_f32_16x16x32_bf16 v[22:25], v[160:163], v[214:217], v[22:25]
	v_mfma_f32_16x16x32_bf16 v[18:21], v[182:185], v[214:217], v[18:21]
	v_mfma_f32_16x16x32_bf16 v[14:17], v[160:163], v[222:225], v[14:17]
	v_mfma_f32_16x16x32_bf16 v[10:13], v[182:185], v[222:225], v[10:13]
	v_mfma_f32_16x16x32_bf16 v[6:9], v[160:163], v[230:233], v[6:9]
	v_mfma_f32_16x16x32_bf16 v[2:5], v[182:185], v[230:233], v[2:5]
	v_mfma_f32_16x16x32_bf16 v[30:33], v[178:181], v[210:213], v[30:33]
	v_mfma_f32_16x16x32_bf16 v[26:29], v[186:189], v[210:213], v[26:29]
	v_mfma_f32_16x16x32_bf16 v[22:25], v[178:181], v[218:221], v[22:25]
	v_mfma_f32_16x16x32_bf16 v[18:21], v[186:189], v[218:221], v[18:21]
	v_mfma_f32_16x16x32_bf16 v[14:17], v[178:181], v[226:229], v[14:17]
	v_mfma_f32_16x16x32_bf16 v[10:13], v[186:189], v[226:229], v[10:13]
	v_mfma_f32_16x16x32_bf16 v[6:9], v[178:181], v[234:237], v[6:9]
	v_mfma_f32_16x16x32_bf16 v[2:5], v[186:189], v[234:237], v[2:5]
	s_barrier
	s_setprio 0
	s_add_i32 s48, 0, 0x18000
	s_add_i32 s49, 0, 0x1c000
	v_add_u32_e32 v156, s48, v1
	v_add_u32_e32 v186, s49, v1
	ds_read_b128 v[130:133], v156
	ds_read_b128 v[134:137], v156 offset:1024
	ds_read_b128 v[150:153], v156 offset:2048
	ds_read_b128 v[156:159], v156 offset:3072
	ds_read_b128 v[160:163], v186
	ds_read_b128 v[178:181], v186 offset:1024
	ds_read_b128 v[182:185], v186 offset:2048
	ds_read_b128 v[186:189], v186 offset:3072
	s_add_u32 s46, s70, 0x80000
	s_addc_u32 s47, s71, 0
	s_mov_b32 m0, s79
	v_lshl_add_u64 v[248:249], s[46:47], 0, v[138:139]
	ds_read_b128 v[206:209], v155 offset:32768
	ds_read_b128 v[210:213], v155 offset:33792
	ds_read_b128 v[214:217], v155 offset:34816
	ds_read_b128 v[218:221], v155 offset:35840
	ds_read_b128 v[222:225], v155 offset:36864
	ds_read_b128 v[226:229], v155 offset:37888
	ds_read_b128 v[230:233], v155 offset:38912
	ds_read_b128 v[234:237], v155 offset:39936
	global_load_lds_dwordx4 v[248:249], off
	v_lshl_add_u64 v[248:249], s[46:47], 0, v[140:141]
	s_mov_b32 m0, s80
	s_nop 0
	global_load_lds_dwordx4 v[248:249], off
	s_waitcnt vmcnt(8)
	s_waitcnt lgkmcnt(0)
	s_setprio 1
	s_waitcnt lgkmcnt(0)
	v_mfma_f32_16x16x32_bf16 v[126:129], v[130:133], v[206:209], v[126:129]
	v_mfma_f32_16x16x32_bf16 v[122:125], v[150:153], v[206:209], v[122:125]
	v_mfma_f32_16x16x32_bf16 v[118:121], v[130:133], v[214:217], v[118:121]
	v_mfma_f32_16x16x32_bf16 v[114:117], v[150:153], v[214:217], v[114:117]
	v_mfma_f32_16x16x32_bf16 v[110:113], v[130:133], v[222:225], v[110:113]
	v_mfma_f32_16x16x32_bf16 v[106:109], v[150:153], v[222:225], v[106:109]
	s_barrier
	v_mfma_f32_16x16x32_bf16 v[102:105], v[130:133], v[230:233], v[102:105]
	v_mfma_f32_16x16x32_bf16 v[98:101], v[150:153], v[230:233], v[98:101]
	v_mfma_f32_16x16x32_bf16 v[126:129], v[134:137], v[210:213], v[126:129]
	v_mfma_f32_16x16x32_bf16 v[122:125], v[156:159], v[210:213], v[122:125]
	v_mfma_f32_16x16x32_bf16 v[118:121], v[134:137], v[218:221], v[118:121]
	v_mfma_f32_16x16x32_bf16 v[114:117], v[156:159], v[218:221], v[114:117]
	v_mfma_f32_16x16x32_bf16 v[110:113], v[134:137], v[226:229], v[110:113]
	v_mfma_f32_16x16x32_bf16 v[106:109], v[156:159], v[226:229], v[106:109]
	v_mfma_f32_16x16x32_bf16 v[102:105], v[134:137], v[234:237], v[102:105]
	v_mfma_f32_16x16x32_bf16 v[98:101], v[156:159], v[234:237], v[98:101]
	v_mfma_f32_16x16x32_bf16 v[66:69], v[160:163], v[206:209], v[66:69]
	v_mfma_f32_16x16x32_bf16 v[58:61], v[182:185], v[206:209], v[58:61]
	v_mfma_f32_16x16x32_bf16 v[54:57], v[160:163], v[214:217], v[54:57]
	v_mfma_f32_16x16x32_bf16 v[50:53], v[182:185], v[214:217], v[50:53]
	v_mfma_f32_16x16x32_bf16 v[46:49], v[160:163], v[222:225], v[46:49]
	v_mfma_f32_16x16x32_bf16 v[42:45], v[182:185], v[222:225], v[42:45]
	v_mfma_f32_16x16x32_bf16 v[38:41], v[160:163], v[230:233], v[38:41]
	v_mfma_f32_16x16x32_bf16 v[34:37], v[182:185], v[230:233], v[34:37]
	v_mfma_f32_16x16x32_bf16 v[66:69], v[178:181], v[210:213], v[66:69]
	v_mfma_f32_16x16x32_bf16 v[58:61], v[186:189], v[210:213], v[58:61]
	v_mfma_f32_16x16x32_bf16 v[54:57], v[178:181], v[218:221], v[54:57]
	v_mfma_f32_16x16x32_bf16 v[50:53], v[186:189], v[218:221], v[50:53]
	v_mfma_f32_16x16x32_bf16 v[46:49], v[178:181], v[226:229], v[46:49]
	v_mfma_f32_16x16x32_bf16 v[42:45], v[186:189], v[226:229], v[42:45]
	v_mfma_f32_16x16x32_bf16 v[38:41], v[178:181], v[234:237], v[38:41]
	v_mfma_f32_16x16x32_bf16 v[34:37], v[186:189], v[234:237], v[34:37]
	s_barrier
	s_setprio 0
	s_add_i32 s46, s48, s77
	v_lshl_add_u64 v[164:165], v[164:165], 0, s[42:43]
	s_mov_b32 m0, s46
	ds_read_b128 v[206:209], v155 offset:49152
	ds_read_b128 v[210:213], v155 offset:50176
	ds_read_b128 v[214:217], v155 offset:51200
	ds_read_b128 v[218:221], v155 offset:52224
	ds_read_b128 v[222:225], v155 offset:53248
	ds_read_b128 v[226:229], v155 offset:54272
	ds_read_b128 v[230:233], v155 offset:55296
	ds_read_b128 v[234:237], v155 offset:56320
	global_load_lds_dwordx4 v[164:165], off
	s_add_i32 m0, s46, 0x2000
	s_add_u32 s46, s60, 0x80080
	v_lshl_add_u64 v[164:165], v[242:243], 0, s[42:43]
	s_addc_u32 s47, s61, 0
	s_add_i32 s48, s49, s77
	global_load_lds_dwordx4 v[164:165], off
	v_lshl_add_u64 v[164:165], s[46:47], 0, v[166:167]
	s_mov_b32 m0, s48
	s_nop 0
	global_load_lds_dwordx4 v[164:165], off
	v_lshl_add_u64 v[164:165], s[46:47], 0, v[142:143]
	s_add_i32 m0, s48, 0x2000
	s_nop 0
	global_load_lds_dwordx4 v[164:165], off
	v_lshl_add_u64 v[164:165], v[244:245], 0, s[42:43]
	s_mov_b32 m0, s26
	s_nop 0
	global_load_lds_dwordx4 v[164:165], off
	v_lshl_add_u64 v[164:165], v[246:247], 0, s[42:43]
	s_mov_b32 m0, s81
	s_nop 0
	global_load_lds_dwordx4 v[164:165], off
	s_waitcnt vmcnt(8)
	s_waitcnt lgkmcnt(0)
	s_setprio 1
	s_waitcnt lgkmcnt(0)
	v_mfma_f32_16x16x32_bf16 v[94:97], v[130:133], v[206:209], v[94:97]
	v_mfma_f32_16x16x32_bf16 v[90:93], v[150:153], v[206:209], v[90:93]
	v_mfma_f32_16x16x32_bf16 v[86:89], v[130:133], v[214:217], v[86:89]
	v_mfma_f32_16x16x32_bf16 v[82:85], v[150:153], v[214:217], v[82:85]
	v_mfma_f32_16x16x32_bf16 v[78:81], v[130:133], v[222:225], v[78:81]
	v_mfma_f32_16x16x32_bf16 v[74:77], v[150:153], v[222:225], v[74:77]
	s_barrier
	v_mfma_f32_16x16x32_bf16 v[70:73], v[130:133], v[230:233], v[70:73]
	v_mfma_f32_16x16x32_bf16 v[62:65], v[150:153], v[230:233], v[62:65]
	v_mfma_f32_16x16x32_bf16 v[94:97], v[134:137], v[210:213], v[94:97]
	v_mfma_f32_16x16x32_bf16 v[90:93], v[156:159], v[210:213], v[90:93]
	v_mfma_f32_16x16x32_bf16 v[86:89], v[134:137], v[218:221], v[86:89]
	v_mfma_f32_16x16x32_bf16 v[82:85], v[156:159], v[218:221], v[82:85]
	v_mfma_f32_16x16x32_bf16 v[78:81], v[134:137], v[226:229], v[78:81]
	v_mfma_f32_16x16x32_bf16 v[74:77], v[156:159], v[226:229], v[74:77]
	v_mfma_f32_16x16x32_bf16 v[70:73], v[134:137], v[234:237], v[70:73]
	v_mfma_f32_16x16x32_bf16 v[62:65], v[156:159], v[234:237], v[62:65]
	v_mfma_f32_16x16x32_bf16 v[30:33], v[160:163], v[206:209], v[30:33]
	v_mfma_f32_16x16x32_bf16 v[26:29], v[182:185], v[206:209], v[26:29]
	v_mfma_f32_16x16x32_bf16 v[22:25], v[160:163], v[214:217], v[22:25]
	v_mfma_f32_16x16x32_bf16 v[18:21], v[182:185], v[214:217], v[18:21]
	v_mfma_f32_16x16x32_bf16 v[14:17], v[160:163], v[222:225], v[14:17]
	v_mfma_f32_16x16x32_bf16 v[10:13], v[182:185], v[222:225], v[10:13]
	v_mfma_f32_16x16x32_bf16 v[6:9], v[160:163], v[230:233], v[6:9]
	v_mfma_f32_16x16x32_bf16 v[2:5], v[182:185], v[230:233], v[2:5]
	v_mfma_f32_16x16x32_bf16 v[30:33], v[178:181], v[210:213], v[30:33]
	v_mfma_f32_16x16x32_bf16 v[26:29], v[186:189], v[210:213], v[26:29]
	v_mfma_f32_16x16x32_bf16 v[22:25], v[178:181], v[218:221], v[22:25]
	v_mfma_f32_16x16x32_bf16 v[18:21], v[186:189], v[218:221], v[18:21]
	v_mfma_f32_16x16x32_bf16 v[14:17], v[178:181], v[226:229], v[14:17]
	v_mfma_f32_16x16x32_bf16 v[10:13], v[186:189], v[226:229], v[10:13]
	v_mfma_f32_16x16x32_bf16 v[6:9], v[178:181], v[234:237], v[6:9]
	v_mfma_f32_16x16x32_bf16 v[2:5], v[186:189], v[234:237], v[2:5]
	s_barrier
	s_setprio 0
	s_add_i32 s87, s87, 2
	s_add_u32 s68, s68, 0x100
	s_addc_u32 s69, s69, 0
	s_add_u32 s85, s85, 0x100
	s_addc_u32 s86, s86, 0
	s_cmp_gt_u32 s87, 29
	s_cbranch_scc0 .LBB0_795
	s_and_b64 vcc, exec, s[12:13]
	s_cbranch_vccz .LBB0_798
	s_barrier

.LBB0_819:
	s_add_i32 s93, s60, 2
	s_add_u32 s46, s72, 0x80
	s_addc_u32 s47, s73, 0
	s_add_i32 s48, 0, 0x10000
	s_cmp_eq_u32 s87, s60
	s_cselect_b32 s61, s23, s47
	s_cselect_b32 s60, s64, s46
	s_cselect_b32 s47, s21, s92
	s_cselect_b32 s46, s90, s91
	s_add_i32 s49, 0, 0x14000
	v_add_u32_e32 v142, s48, v205
	v_add_u32_e32 v182, s49, v205
	ds_read_b128 v[130:133], v142
	ds_read_b128 v[134:137], v142 offset:1024
	ds_read_b128 v[138:141], v142 offset:2048
	ds_read_b128 v[142:145], v142 offset:3072
	ds_read_b128 v[146:149], v182
	ds_read_b128 v[150:153], v182 offset:1024
	ds_read_b128 v[178:181], v182 offset:2048
	ds_read_b128 v[182:185], v182 offset:3072
	v_lshl_add_u64 v[236:237], s[72:73], 0, v[162:163]
	s_add_i32 m0, s71, 0xc000
	ds_read_b128 v[186:189], v207
	ds_read_b128 v[208:211], v207 offset:1024
	ds_read_b128 v[212:215], v207 offset:2048
	ds_read_b128 v[216:219], v207 offset:3072
	ds_read_b128 v[220:223], v207 offset:4096
	ds_read_b128 v[224:227], v207 offset:5120
	ds_read_b128 v[228:231], v207 offset:6144
	ds_read_b128 v[232:235], v207 offset:7168
	global_load_lds_dwordx4 v[236:237], off
	v_lshl_add_u64 v[236:237], s[72:73], 0, v[164:165]
	s_add_i32 m0, s71, 0xe000
	s_nop 0
	global_load_lds_dwordx4 v[236:237], off
	s_waitcnt vmcnt(8)
	s_waitcnt lgkmcnt(0)
	s_setprio 1
	s_waitcnt lgkmcnt(0)
	v_mfma_f32_16x16x32_bf16 v[126:129], v[130:133], v[186:189], v[126:129]
	v_mfma_f32_16x16x32_bf16 v[122:125], v[138:141], v[186:189], v[122:125]
	v_mfma_f32_16x16x32_bf16 v[118:121], v[130:133], v[212:215], v[118:121]
	v_mfma_f32_16x16x32_bf16 v[114:117], v[138:141], v[212:215], v[114:117]
	v_mfma_f32_16x16x32_bf16 v[110:113], v[130:133], v[220:223], v[110:113]
	v_mfma_f32_16x16x32_bf16 v[106:109], v[138:141], v[220:223], v[106:109]
	s_barrier
	v_mfma_f32_16x16x32_bf16 v[102:105], v[130:133], v[228:231], v[102:105]
	v_mfma_f32_16x16x32_bf16 v[98:101], v[138:141], v[228:231], v[98:101]
	v_mfma_f32_16x16x32_bf16 v[126:129], v[134:137], v[208:211], v[126:129]
	v_mfma_f32_16x16x32_bf16 v[122:125], v[142:145], v[208:211], v[122:125]
	v_mfma_f32_16x16x32_bf16 v[118:121], v[134:137], v[216:219], v[118:121]
	v_mfma_f32_16x16x32_bf16 v[114:117], v[142:145], v[216:219], v[114:117]
	v_mfma_f32_16x16x32_bf16 v[110:113], v[134:137], v[224:227], v[110:113]
	v_mfma_f32_16x16x32_bf16 v[106:109], v[142:145], v[224:227], v[106:109]
	v_mfma_f32_16x16x32_bf16 v[102:105], v[134:137], v[232:235], v[102:105]
	v_mfma_f32_16x16x32_bf16 v[98:101], v[142:145], v[232:235], v[98:101]
	v_mfma_f32_16x16x32_bf16 v[94:97], v[146:149], v[186:189], v[94:97]
	v_mfma_f32_16x16x32_bf16 v[90:93], v[178:181], v[186:189], v[90:93]
	v_mfma_f32_16x16x32_bf16 v[86:89], v[146:149], v[212:215], v[86:89]
	v_mfma_f32_16x16x32_bf16 v[82:85], v[178:181], v[212:215], v[82:85]
	v_mfma_f32_16x16x32_bf16 v[78:81], v[146:149], v[220:223], v[78:81]
	v_mfma_f32_16x16x32_bf16 v[74:77], v[178:181], v[220:223], v[74:77]
	v_mfma_f32_16x16x32_bf16 v[70:73], v[146:149], v[228:231], v[70:73]
	v_mfma_f32_16x16x32_bf16 v[66:69], v[178:181], v[228:231], v[66:69]
	v_mfma_f32_16x16x32_bf16 v[94:97], v[150:153], v[208:211], v[94:97]
	v_mfma_f32_16x16x32_bf16 v[90:93], v[182:185], v[208:211], v[90:93]
	v_mfma_f32_16x16x32_bf16 v[86:89], v[150:153], v[216:219], v[86:89]
	v_mfma_f32_16x16x32_bf16 v[82:85], v[182:185], v[216:219], v[82:85]
	v_mfma_f32_16x16x32_bf16 v[78:81], v[150:153], v[224:227], v[78:81]
	v_mfma_f32_16x16x32_bf16 v[74:77], v[182:185], v[224:227], v[74:77]
	v_mfma_f32_16x16x32_bf16 v[70:73], v[150:153], v[232:235], v[70:73]
	v_mfma_f32_16x16x32_bf16 v[66:69], v[182:185], v[232:235], v[66:69]
	s_barrier
	s_setprio 0
	s_add_i32 s48, s48, s80
	v_lshl_add_u64 v[236:237], s[46:47], 0, v[166:167]
	s_mov_b32 m0, s48
	ds_read_b128 v[186:189], v207 offset:16384
	ds_read_b128 v[208:211], v207 offset:17408
	ds_read_b128 v[212:215], v207 offset:18432
	ds_read_b128 v[216:219], v207 offset:19456
	ds_read_b128 v[220:223], v207 offset:20480
	ds_read_b128 v[224:227], v207 offset:21504
	ds_read_b128 v[228:231], v207 offset:22528
	ds_read_b128 v[232:235], v207 offset:23552
	global_load_lds_dwordx4 v[236:237], off
	s_add_i32 m0, s48, 0x2000
	v_lshl_add_u64 v[242:243], s[46:47], 0, v[158:159]
	s_add_u32 s46, s46, s26
	s_addc_u32 s47, s47, 0
	s_add_i32 s48, s49, s80
	global_load_lds_dwordx4 v[242:243], off
	v_lshl_add_u64 v[244:245], s[46:47], 0, v[166:167]
	s_mov_b32 m0, s48
	v_lshl_add_u64 v[246:247], s[46:47], 0, v[158:159]
	global_load_lds_dwordx4 v[244:245], off
	s_add_i32 m0, s48, 0x2000
	v_lshl_add_u64 v[248:249], s[60:61], 0, v[154:155]
	global_load_lds_dwordx4 v[246:247], off
	s_mov_b32 m0, s71
	v_lshl_add_u64 v[250:251], s[60:61], 0, v[156:157]
	global_load_lds_dwordx4 v[248:249], off
	s_mov_b32 m0, s81
	s_nop 0
	global_load_lds_dwordx4 v[250:251], off
	s_waitcnt vmcnt(8)
	s_waitcnt lgkmcnt(0)
	s_setprio 1
	s_waitcnt lgkmcnt(0)
	v_mfma_f32_16x16x32_bf16 v[62:65], v[130:133], v[186:189], v[62:65]
	v_mfma_f32_16x16x32_bf16 v[58:61], v[138:141], v[186:189], v[58:61]
	v_mfma_f32_16x16x32_bf16 v[54:57], v[130:133], v[212:215], v[54:57]
	v_mfma_f32_16x16x32_bf16 v[50:53], v[138:141], v[212:215], v[50:53]
	v_mfma_f32_16x16x32_bf16 v[46:49], v[130:133], v[220:223], v[46:49]
	v_mfma_f32_16x16x32_bf16 v[42:45], v[138:141], v[220:223], v[42:45]
	s_barrier
	v_mfma_f32_16x16x32_bf16 v[38:41], v[130:133], v[228:231], v[38:41]
	v_mfma_f32_16x16x32_bf16 v[34:37], v[138:141], v[228:231], v[34:37]
	v_mfma_f32_16x16x32_bf16 v[62:65], v[134:137], v[208:211], v[62:65]
	v_mfma_f32_16x16x32_bf16 v[58:61], v[142:145], v[208:211], v[58:61]
	v_mfma_f32_16x16x32_bf16 v[54:57], v[134:137], v[216:219], v[54:57]
	v_mfma_f32_16x16x32_bf16 v[50:53], v[142:145], v[216:219], v[50:53]
	v_mfma_f32_16x16x32_bf16 v[46:49], v[134:137], v[224:227], v[46:49]
	v_mfma_f32_16x16x32_bf16 v[42:45], v[142:145], v[224:227], v[42:45]
	v_mfma_f32_16x16x32_bf16 v[38:41], v[134:137], v[232:235], v[38:41]
	v_mfma_f32_16x16x32_bf16 v[34:37], v[142:145], v[232:235], v[34:37]
	v_mfma_f32_16x16x32_bf16 v[30:33], v[146:149], v[186:189], v[30:33]
	v_mfma_f32_16x16x32_bf16 v[26:29], v[178:181], v[186:189], v[26:29]
	v_mfma_f32_16x16x32_bf16 v[22:25], v[146:149], v[212:215], v[22:25]
	v_mfma_f32_16x16x32_bf16 v[18:21], v[178:181], v[212:215], v[18:21]
	v_mfma_f32_16x16x32_bf16 v[14:17], v[146:149], v[220:223], v[14:17]
	v_mfma_f32_16x16x32_bf16 v[10:13], v[178:181], v[220:223], v[10:13]
	v_mfma_f32_16x16x32_bf16 v[6:9], v[146:149], v[228:231], v[6:9]
	v_mfma_f32_16x16x32_bf16 v[2:5], v[178:181], v[228:231], v[2:5]
	v_mfma_f32_16x16x32_bf16 v[30:33], v[150:153], v[208:211], v[30:33]
	v_mfma_f32_16x16x32_bf16 v[26:29], v[182:185], v[208:211], v[26:29]
	v_mfma_f32_16x16x32_bf16 v[22:25], v[150:153], v[216:219], v[22:25]
	v_mfma_f32_16x16x32_bf16 v[18:21], v[182:185], v[216:219], v[18:21]
	v_mfma_f32_16x16x32_bf16 v[14:17], v[150:153], v[224:227], v[14:17]
	v_mfma_f32_16x16x32_bf16 v[10:13], v[182:185], v[224:227], v[10:13]
	v_mfma_f32_16x16x32_bf16 v[6:9], v[150:153], v[232:235], v[6:9]
	v_mfma_f32_16x16x32_bf16 v[2:5], v[182:185], v[232:235], v[2:5]
	s_barrier
	s_setprio 0
	s_add_i32 s48, 0, 0x18000
	s_add_i32 s49, 0, 0x1c000
	v_add_u32_e32 v142, s48, v205
	v_add_u32_e32 v182, s49, v205
	ds_read_b128 v[130:133], v142
	ds_read_b128 v[134:137], v142 offset:1024
	ds_read_b128 v[138:141], v142 offset:2048
	ds_read_b128 v[142:145], v142 offset:3072
	ds_read_b128 v[146:149], v182
	ds_read_b128 v[150:153], v182 offset:1024
	ds_read_b128 v[178:181], v182 offset:2048
	ds_read_b128 v[182:185], v182 offset:3072
	s_add_u32 s46, s60, s26
	s_addc_u32 s47, s61, 0
	s_mov_b32 m0, s82
	v_lshl_add_u64 v[252:253], s[46:47], 0, v[154:155]
	ds_read_b128 v[186:189], v207 offset:32768
	ds_read_b128 v[208:211], v207 offset:33792
	ds_read_b128 v[212:215], v207 offset:34816
	ds_read_b128 v[216:219], v207 offset:35840
	ds_read_b128 v[220:223], v207 offset:36864
	ds_read_b128 v[224:227], v207 offset:37888
	ds_read_b128 v[228:231], v207 offset:38912
	ds_read_b128 v[232:235], v207 offset:39936
	global_load_lds_dwordx4 v[252:253], off
	v_lshl_add_u64 v[252:253], s[46:47], 0, v[156:157]
	s_mov_b32 m0, s83
	s_nop 0
	global_load_lds_dwordx4 v[252:253], off
	s_waitcnt vmcnt(8)
	s_waitcnt lgkmcnt(0)
	s_setprio 1
	s_waitcnt lgkmcnt(0)
	v_mfma_f32_16x16x32_bf16 v[126:129], v[130:133], v[186:189], v[126:129]
	v_mfma_f32_16x16x32_bf16 v[122:125], v[138:141], v[186:189], v[122:125]
	v_mfma_f32_16x16x32_bf16 v[118:121], v[130:133], v[212:215], v[118:121]
	v_mfma_f32_16x16x32_bf16 v[114:117], v[138:141], v[212:215], v[114:117]
	v_mfma_f32_16x16x32_bf16 v[110:113], v[130:133], v[220:223], v[110:113]
	v_mfma_f32_16x16x32_bf16 v[106:109], v[138:141], v[220:223], v[106:109]
	s_barrier
	v_mfma_f32_16x16x32_bf16 v[102:105], v[130:133], v[228:231], v[102:105]
	v_mfma_f32_16x16x32_bf16 v[98:101], v[138:141], v[228:231], v[98:101]
	v_mfma_f32_16x16x32_bf16 v[126:129], v[134:137], v[208:211], v[126:129]
	v_mfma_f32_16x16x32_bf16 v[122:125], v[142:145], v[208:211], v[122:125]
	v_mfma_f32_16x16x32_bf16 v[118:121], v[134:137], v[216:219], v[118:121]
	v_mfma_f32_16x16x32_bf16 v[114:117], v[142:145], v[216:219], v[114:117]
	v_mfma_f32_16x16x32_bf16 v[110:113], v[134:137], v[224:227], v[110:113]
	v_mfma_f32_16x16x32_bf16 v[106:109], v[142:145], v[224:227], v[106:109]
	v_mfma_f32_16x16x32_bf16 v[102:105], v[134:137], v[232:235], v[102:105]
	v_mfma_f32_16x16x32_bf16 v[98:101], v[142:145], v[232:235], v[98:101]
	v_mfma_f32_16x16x32_bf16 v[94:97], v[146:149], v[186:189], v[94:97]
	v_mfma_f32_16x16x32_bf16 v[90:93], v[178:181], v[186:189], v[90:93]
	v_mfma_f32_16x16x32_bf16 v[86:89], v[146:149], v[212:215], v[86:89]
	v_mfma_f32_16x16x32_bf16 v[82:85], v[178:181], v[212:215], v[82:85]
	v_mfma_f32_16x16x32_bf16 v[78:81], v[146:149], v[220:223], v[78:81]
	v_mfma_f32_16x16x32_bf16 v[74:77], v[178:181], v[220:223], v[74:77]
	v_mfma_f32_16x16x32_bf16 v[70:73], v[146:149], v[228:231], v[70:73]
	v_mfma_f32_16x16x32_bf16 v[66:69], v[178:181], v[228:231], v[66:69]
	v_mfma_f32_16x16x32_bf16 v[94:97], v[150:153], v[208:211], v[94:97]
	v_mfma_f32_16x16x32_bf16 v[90:93], v[182:185], v[208:211], v[90:93]
	v_mfma_f32_16x16x32_bf16 v[86:89], v[150:153], v[216:219], v[86:89]
	v_mfma_f32_16x16x32_bf16 v[82:85], v[182:185], v[216:219], v[82:85]
	v_mfma_f32_16x16x32_bf16 v[78:81], v[150:153], v[224:227], v[78:81]
	v_mfma_f32_16x16x32_bf16 v[74:77], v[182:185], v[224:227], v[74:77]
	v_mfma_f32_16x16x32_bf16 v[70:73], v[150:153], v[232:235], v[70:73]
	v_mfma_f32_16x16x32_bf16 v[66:69], v[182:185], v[232:235], v[66:69]
	s_barrier
	s_setprio 0
	s_add_i32 s46, s48, s80
	v_lshl_add_u64 v[236:237], v[236:237], 0, s[42:43]
	s_mov_b32 m0, s46
	ds_read_b128 v[186:189], v207 offset:49152
	ds_read_b128 v[208:211], v207 offset:50176
	ds_read_b128 v[212:215], v207 offset:51200
	ds_read_b128 v[216:219], v207 offset:52224
	ds_read_b128 v[220:223], v207 offset:53248
	ds_read_b128 v[224:227], v207 offset:54272
	ds_read_b128 v[228:231], v207 offset:55296
	ds_read_b128 v[232:235], v207 offset:56320
	global_load_lds_dwordx4 v[236:237], off
	v_lshl_add_u64 v[236:237], v[242:243], 0, s[42:43]
	s_add_i32 m0, s46, 0x2000
	s_add_i32 s46, s49, s80
	global_load_lds_dwordx4 v[236:237], off
	v_lshl_add_u64 v[236:237], v[244:245], 0, s[42:43]
	s_mov_b32 m0, s46
	s_nop 0
	global_load_lds_dwordx4 v[236:237], off
	v_lshl_add_u64 v[236:237], v[246:247], 0, s[42:43]
	s_add_i32 m0, s46, 0x2000
	s_nop 0
	global_load_lds_dwordx4 v[236:237], off
	v_lshl_add_u64 v[236:237], v[248:249], 0, s[42:43]
	s_mov_b32 m0, s85
	s_nop 0
	global_load_lds_dwordx4 v[236:237], off
	v_lshl_add_u64 v[236:237], v[250:251], 0, s[42:43]
	s_mov_b32 m0, s86
	s_nop 0
	global_load_lds_dwordx4 v[236:237], off
	s_waitcnt vmcnt(8)
	s_waitcnt lgkmcnt(0)
	s_setprio 1
	s_waitcnt lgkmcnt(0)
	v_mfma_f32_16x16x32_bf16 v[62:65], v[130:133], v[186:189], v[62:65]
	v_mfma_f32_16x16x32_bf16 v[58:61], v[138:141], v[186:189], v[58:61]
	v_mfma_f32_16x16x32_bf16 v[54:57], v[130:133], v[212:215], v[54:57]
	v_mfma_f32_16x16x32_bf16 v[50:53], v[138:141], v[212:215], v[50:53]
	v_mfma_f32_16x16x32_bf16 v[46:49], v[130:133], v[220:223], v[46:49]
	v_mfma_f32_16x16x32_bf16 v[42:45], v[138:141], v[220:223], v[42:45]
	s_barrier
	v_mfma_f32_16x16x32_bf16 v[38:41], v[130:133], v[228:231], v[38:41]
	v_mfma_f32_16x16x32_bf16 v[34:37], v[138:141], v[228:231], v[34:37]
	v_mfma_f32_16x16x32_bf16 v[62:65], v[134:137], v[208:211], v[62:65]
	v_mfma_f32_16x16x32_bf16 v[58:61], v[142:145], v[208:211], v[58:61]
	v_mfma_f32_16x16x32_bf16 v[54:57], v[134:137], v[216:219], v[54:57]
	v_mfma_f32_16x16x32_bf16 v[50:53], v[142:145], v[216:219], v[50:53]
	v_mfma_f32_16x16x32_bf16 v[46:49], v[134:137], v[224:227], v[46:49]
	v_mfma_f32_16x16x32_bf16 v[42:45], v[142:145], v[224:227], v[42:45]
	v_mfma_f32_16x16x32_bf16 v[38:41], v[134:137], v[232:235], v[38:41]
	v_mfma_f32_16x16x32_bf16 v[34:37], v[142:145], v[232:235], v[34:37]
	v_mfma_f32_16x16x32_bf16 v[30:33], v[146:149], v[186:189], v[30:33]
	v_mfma_f32_16x16x32_bf16 v[26:29], v[178:181], v[186:189], v[26:29]
	v_mfma_f32_16x16x32_bf16 v[22:25], v[146:149], v[212:215], v[22:25]
	v_mfma_f32_16x16x32_bf16 v[18:21], v[178:181], v[212:215], v[18:21]
	v_mfma_f32_16x16x32_bf16 v[14:17], v[146:149], v[220:223], v[14:17]
	v_mfma_f32_16x16x32_bf16 v[10:13], v[178:181], v[220:223], v[10:13]
	v_mfma_f32_16x16x32_bf16 v[6:9], v[146:149], v[228:231], v[6:9]
	v_mfma_f32_16x16x32_bf16 v[2:5], v[178:181], v[228:231], v[2:5]
	v_mfma_f32_16x16x32_bf16 v[30:33], v[150:153], v[208:211], v[30:33]
	v_mfma_f32_16x16x32_bf16 v[26:29], v[182:185], v[208:211], v[26:29]
	v_mfma_f32_16x16x32_bf16 v[22:25], v[150:153], v[216:219], v[22:25]
	v_mfma_f32_16x16x32_bf16 v[18:21], v[182:185], v[216:219], v[18:21]
	v_mfma_f32_16x16x32_bf16 v[14:17], v[150:153], v[224:227], v[14:17]
	v_mfma_f32_16x16x32_bf16 v[10:13], v[182:185], v[224:227], v[10:13]
	v_mfma_f32_16x16x32_bf16 v[6:9], v[150:153], v[232:235], v[6:9]
	v_mfma_f32_16x16x32_bf16 v[2:5], v[182:185], v[232:235], v[2:5]
	s_barrier
	s_setprio 0
	s_add_u32 s72, s72, 0x100
	s_addc_u32 s73, s73, 0
	s_add_u32 s91, s91, 0x100
	s_addc_u32 s92, s92, 0
	s_cmp_ge_u32 s93, s84
	s_mov_b32 s60, s93
	s_cbranch_scc0 .LBB0_819
	s_and_b64 vcc, exec, s[18:19]
	s_cbranch_vccz .LBB0_822
	s_barrier

.LBB0_903:
	s_add_u32 s46, s66, 0xfff80080
	s_addc_u32 s47, s67, -1
	s_add_i32 s48, 0, 0x10000
	s_cmp_eq_u32 s84, 28
	s_cselect_b32 s69, s17, s47
	s_cselect_b32 s68, s64, s46
	s_cselect_b32 s61, s13, s83
	s_cselect_b32 s60, s81, s82
	s_add_i32 s49, 0, 0x14000
	v_add_u32_e32 v142, s48, v186
	v_add_u32_e32 v164, s49, v186
	ds_read_b128 v[130:133], v142
	ds_read_b128 v[134:137], v142 offset:1024
	ds_read_b128 v[138:141], v142 offset:2048
	ds_read_b128 v[142:145], v142 offset:3072
	ds_read_b128 v[146:149], v164
	ds_read_b128 v[160:163], v164 offset:1024
	ds_read_b128 v[178:181], v164 offset:2048
	ds_read_b128 v[182:185], v164 offset:3072
	v_lshl_add_u64 v[164:165], s[66:67], 0, v[156:157]
	s_add_i32 m0, s74, 0xc000
	ds_read_b128 v[206:209], v188
	ds_read_b128 v[210:213], v188 offset:1024
	ds_read_b128 v[214:217], v188 offset:2048
	ds_read_b128 v[218:221], v188 offset:3072
	ds_read_b128 v[222:225], v188 offset:4096
	ds_read_b128 v[226:229], v188 offset:5120
	ds_read_b128 v[230:233], v188 offset:6144
	ds_read_b128 v[234:237], v188 offset:7168
	global_load_lds_dwordx4 v[164:165], off
	v_lshl_add_u64 v[164:165], s[66:67], 0, v[158:159]
	s_add_i32 m0, s74, 0xe000
	s_nop 0
	global_load_lds_dwordx4 v[164:165], off
	s_waitcnt vmcnt(8)
	s_waitcnt lgkmcnt(0)
	s_setprio 1
	s_waitcnt lgkmcnt(0)
	v_mfma_f32_16x16x32_bf16 v[126:129], v[130:133], v[206:209], v[126:129]
	v_mfma_f32_16x16x32_bf16 v[122:125], v[138:141], v[206:209], v[122:125]
	v_mfma_f32_16x16x32_bf16 v[118:121], v[130:133], v[214:217], v[118:121]
	v_mfma_f32_16x16x32_bf16 v[110:113], v[138:141], v[214:217], v[110:113]
	v_mfma_f32_16x16x32_bf16 v[94:97], v[130:133], v[222:225], v[94:97]
	v_mfma_f32_16x16x32_bf16 v[90:93], v[138:141], v[222:225], v[90:93]
	s_barrier
	v_mfma_f32_16x16x32_bf16 v[82:85], v[130:133], v[230:233], v[82:85]
	v_mfma_f32_16x16x32_bf16 v[74:77], v[138:141], v[230:233], v[74:77]
	v_mfma_f32_16x16x32_bf16 v[126:129], v[134:137], v[210:213], v[126:129]
	v_mfma_f32_16x16x32_bf16 v[122:125], v[142:145], v[210:213], v[122:125]
	v_mfma_f32_16x16x32_bf16 v[118:121], v[134:137], v[218:221], v[118:121]
	v_mfma_f32_16x16x32_bf16 v[110:113], v[142:145], v[218:221], v[110:113]
	v_mfma_f32_16x16x32_bf16 v[94:97], v[134:137], v[226:229], v[94:97]
	v_mfma_f32_16x16x32_bf16 v[90:93], v[142:145], v[226:229], v[90:93]
	v_mfma_f32_16x16x32_bf16 v[82:85], v[134:137], v[234:237], v[82:85]
	v_mfma_f32_16x16x32_bf16 v[74:77], v[142:145], v[234:237], v[74:77]
	v_mfma_f32_16x16x32_bf16 v[114:117], v[146:149], v[206:209], v[114:117]
	v_mfma_f32_16x16x32_bf16 v[106:109], v[178:181], v[206:209], v[106:109]
	v_mfma_f32_16x16x32_bf16 v[102:105], v[146:149], v[214:217], v[102:105]
	v_mfma_f32_16x16x32_bf16 v[98:101], v[178:181], v[214:217], v[98:101]
	v_mfma_f32_16x16x32_bf16 v[86:89], v[146:149], v[222:225], v[86:89]
	v_mfma_f32_16x16x32_bf16 v[78:81], v[178:181], v[222:225], v[78:81]
	v_mfma_f32_16x16x32_bf16 v[70:73], v[146:149], v[230:233], v[70:73]
	v_mfma_f32_16x16x32_bf16 v[66:69], v[178:181], v[230:233], v[66:69]
	v_mfma_f32_16x16x32_bf16 v[114:117], v[160:163], v[210:213], v[114:117]
	v_mfma_f32_16x16x32_bf16 v[106:109], v[182:185], v[210:213], v[106:109]
	v_mfma_f32_16x16x32_bf16 v[102:105], v[160:163], v[218:221], v[102:105]
	v_mfma_f32_16x16x32_bf16 v[98:101], v[182:185], v[218:221], v[98:101]
	v_mfma_f32_16x16x32_bf16 v[86:89], v[160:163], v[226:229], v[86:89]
	v_mfma_f32_16x16x32_bf16 v[78:81], v[182:185], v[226:229], v[78:81]
	v_mfma_f32_16x16x32_bf16 v[70:73], v[160:163], v[234:237], v[70:73]
	v_mfma_f32_16x16x32_bf16 v[66:69], v[182:185], v[234:237], v[66:69]
	s_barrier
	s_setprio 0
	s_add_i32 s46, s48, s73
	v_lshl_add_u64 v[164:165], s[60:61], 0, v[166:167]
	s_mov_b32 m0, s46
	ds_read_b128 v[206:209], v188 offset:16384
	ds_read_b128 v[210:213], v188 offset:17408
	ds_read_b128 v[214:217], v188 offset:18432
	ds_read_b128 v[218:221], v188 offset:19456
	ds_read_b128 v[222:225], v188 offset:20480
	ds_read_b128 v[226:229], v188 offset:21504
	ds_read_b128 v[230:233], v188 offset:22528
	ds_read_b128 v[234:237], v188 offset:23552
	global_load_lds_dwordx4 v[164:165], off
	s_add_i32 m0, s46, 0x2000
	s_add_u32 s46, s60, 0x80000
	v_lshl_add_u64 v[242:243], s[60:61], 0, v[154:155]
	s_addc_u32 s47, s61, 0
	s_add_i32 s48, s49, s73
	global_load_lds_dwordx4 v[242:243], off
	v_lshl_add_u64 v[244:245], s[46:47], 0, v[166:167]
	s_mov_b32 m0, s48
	v_lshl_add_u64 v[246:247], s[68:69], 0, v[152:153]
	global_load_lds_dwordx4 v[244:245], off
	v_lshl_add_u64 v[244:245], s[46:47], 0, v[154:155]
	s_add_i32 m0, s48, 0x2000
	s_nop 0
	global_load_lds_dwordx4 v[244:245], off
	v_lshl_add_u64 v[244:245], s[68:69], 0, v[150:151]
	s_mov_b32 m0, s74
	s_nop 0
	global_load_lds_dwordx4 v[244:245], off
	s_mov_b32 m0, s75
	s_nop 0
	global_load_lds_dwordx4 v[246:247], off
	s_waitcnt vmcnt(8)
	s_waitcnt lgkmcnt(0)
	s_setprio 1
	s_waitcnt lgkmcnt(0)
	v_mfma_f32_16x16x32_bf16 v[62:65], v[130:133], v[206:209], v[62:65]
	v_mfma_f32_16x16x32_bf16 v[58:61], v[138:141], v[206:209], v[58:61]
	v_mfma_f32_16x16x32_bf16 v[50:53], v[130:133], v[214:217], v[50:53]
	v_mfma_f32_16x16x32_bf16 v[42:45], v[138:141], v[214:217], v[42:45]
	v_mfma_f32_16x16x32_bf16 v[34:37], v[130:133], v[222:225], v[34:37]
	v_mfma_f32_16x16x32_bf16 v[26:29], v[138:141], v[222:225], v[26:29]
	s_barrier
	v_mfma_f32_16x16x32_bf16 v[18:21], v[130:133], v[230:233], v[18:21]
	v_mfma_f32_16x16x32_bf16 v[10:13], v[138:141], v[230:233], v[10:13]
	v_mfma_f32_16x16x32_bf16 v[62:65], v[134:137], v[210:213], v[62:65]
	v_mfma_f32_16x16x32_bf16 v[58:61], v[142:145], v[210:213], v[58:61]
	v_mfma_f32_16x16x32_bf16 v[50:53], v[134:137], v[218:221], v[50:53]
	v_mfma_f32_16x16x32_bf16 v[42:45], v[142:145], v[218:221], v[42:45]
	v_mfma_f32_16x16x32_bf16 v[34:37], v[134:137], v[226:229], v[34:37]
	v_mfma_f32_16x16x32_bf16 v[26:29], v[142:145], v[226:229], v[26:29]
	v_mfma_f32_16x16x32_bf16 v[18:21], v[134:137], v[234:237], v[18:21]
	v_mfma_f32_16x16x32_bf16 v[10:13], v[142:145], v[234:237], v[10:13]
	v_mfma_f32_16x16x32_bf16 v[54:57], v[146:149], v[206:209], v[54:57]
	v_mfma_f32_16x16x32_bf16 v[46:49], v[178:181], v[206:209], v[46:49]
	v_mfma_f32_16x16x32_bf16 v[38:41], v[146:149], v[214:217], v[38:41]
	v_mfma_f32_16x16x32_bf16 v[30:33], v[178:181], v[214:217], v[30:33]
	v_mfma_f32_16x16x32_bf16 v[22:25], v[146:149], v[222:225], v[22:25]
	v_mfma_f32_16x16x32_bf16 v[14:17], v[178:181], v[222:225], v[14:17]
	v_mfma_f32_16x16x32_bf16 v[6:9], v[146:149], v[230:233], v[6:9]
	v_mfma_f32_16x16x32_bf16 v[2:5], v[178:181], v[230:233], v[2:5]
	v_mfma_f32_16x16x32_bf16 v[54:57], v[160:163], v[210:213], v[54:57]
	v_mfma_f32_16x16x32_bf16 v[46:49], v[182:185], v[210:213], v[46:49]
	v_mfma_f32_16x16x32_bf16 v[38:41], v[160:163], v[218:221], v[38:41]
	v_mfma_f32_16x16x32_bf16 v[30:33], v[182:185], v[218:221], v[30:33]
	v_mfma_f32_16x16x32_bf16 v[22:25], v[160:163], v[226:229], v[22:25]
	v_mfma_f32_16x16x32_bf16 v[14:17], v[182:185], v[226:229], v[14:17]
	v_mfma_f32_16x16x32_bf16 v[6:9], v[160:163], v[234:237], v[6:9]
	v_mfma_f32_16x16x32_bf16 v[2:5], v[182:185], v[234:237], v[2:5]
	s_barrier
	s_setprio 0
	s_add_i32 s48, 0, 0x18000
	s_add_i32 s49, 0, 0x1c000
	v_add_u32_e32 v142, s48, v186
	v_add_u32_e32 v182, s49, v186
	ds_read_b128 v[130:133], v142
	ds_read_b128 v[134:137], v142 offset:1024
	ds_read_b128 v[138:141], v142 offset:2048
	ds_read_b128 v[142:145], v142 offset:3072
	ds_read_b128 v[146:149], v182
	ds_read_b128 v[160:163], v182 offset:1024
	ds_read_b128 v[178:181], v182 offset:2048
	ds_read_b128 v[182:185], v182 offset:3072
	s_add_u32 s46, s68, 0x80000
	s_addc_u32 s47, s69, 0
	s_mov_b32 m0, s76
	v_lshl_add_u64 v[248:249], s[46:47], 0, v[150:151]
	ds_read_b128 v[206:209], v188 offset:32768
	ds_read_b128 v[210:213], v188 offset:33792
	ds_read_b128 v[214:217], v188 offset:34816
	ds_read_b128 v[218:221], v188 offset:35840
	ds_read_b128 v[222:225], v188 offset:36864
	ds_read_b128 v[226:229], v188 offset:37888
	ds_read_b128 v[230:233], v188 offset:38912
	ds_read_b128 v[234:237], v188 offset:39936
	global_load_lds_dwordx4 v[248:249], off
	v_lshl_add_u64 v[248:249], s[46:47], 0, v[152:153]
	s_mov_b32 m0, s77
	s_nop 0
	global_load_lds_dwordx4 v[248:249], off
	s_waitcnt vmcnt(8)
	s_waitcnt lgkmcnt(0)
	s_setprio 1
	s_waitcnt lgkmcnt(0)
	v_mfma_f32_16x16x32_bf16 v[126:129], v[130:133], v[206:209], v[126:129]
	v_mfma_f32_16x16x32_bf16 v[122:125], v[138:141], v[206:209], v[122:125]
	v_mfma_f32_16x16x32_bf16 v[118:121], v[130:133], v[214:217], v[118:121]
	v_mfma_f32_16x16x32_bf16 v[110:113], v[138:141], v[214:217], v[110:113]
	v_mfma_f32_16x16x32_bf16 v[94:97], v[130:133], v[222:225], v[94:97]
	v_mfma_f32_16x16x32_bf16 v[90:93], v[138:141], v[222:225], v[90:93]
	s_barrier
	v_mfma_f32_16x16x32_bf16 v[82:85], v[130:133], v[230:233], v[82:85]
	v_mfma_f32_16x16x32_bf16 v[74:77], v[138:141], v[230:233], v[74:77]
	v_mfma_f32_16x16x32_bf16 v[126:129], v[134:137], v[210:213], v[126:129]
	v_mfma_f32_16x16x32_bf16 v[122:125], v[142:145], v[210:213], v[122:125]
	v_mfma_f32_16x16x32_bf16 v[118:121], v[134:137], v[218:221], v[118:121]
	v_mfma_f32_16x16x32_bf16 v[110:113], v[142:145], v[218:221], v[110:113]
	v_mfma_f32_16x16x32_bf16 v[94:97], v[134:137], v[226:229], v[94:97]
	v_mfma_f32_16x16x32_bf16 v[90:93], v[142:145], v[226:229], v[90:93]
	v_mfma_f32_16x16x32_bf16 v[82:85], v[134:137], v[234:237], v[82:85]
	v_mfma_f32_16x16x32_bf16 v[74:77], v[142:145], v[234:237], v[74:77]
	v_mfma_f32_16x16x32_bf16 v[114:117], v[146:149], v[206:209], v[114:117]
	v_mfma_f32_16x16x32_bf16 v[106:109], v[178:181], v[206:209], v[106:109]
	v_mfma_f32_16x16x32_bf16 v[102:105], v[146:149], v[214:217], v[102:105]
	v_mfma_f32_16x16x32_bf16 v[98:101], v[178:181], v[214:217], v[98:101]
	v_mfma_f32_16x16x32_bf16 v[86:89], v[146:149], v[222:225], v[86:89]
	v_mfma_f32_16x16x32_bf16 v[78:81], v[178:181], v[222:225], v[78:81]
	v_mfma_f32_16x16x32_bf16 v[70:73], v[146:149], v[230:233], v[70:73]
	v_mfma_f32_16x16x32_bf16 v[66:69], v[178:181], v[230:233], v[66:69]
	v_mfma_f32_16x16x32_bf16 v[114:117], v[160:163], v[210:213], v[114:117]
	v_mfma_f32_16x16x32_bf16 v[106:109], v[182:185], v[210:213], v[106:109]
	v_mfma_f32_16x16x32_bf16 v[102:105], v[160:163], v[218:221], v[102:105]
	v_mfma_f32_16x16x32_bf16 v[98:101], v[182:185], v[218:221], v[98:101]
	v_mfma_f32_16x16x32_bf16 v[86:89], v[160:163], v[226:229], v[86:89]
	v_mfma_f32_16x16x32_bf16 v[78:81], v[182:185], v[226:229], v[78:81]
	v_mfma_f32_16x16x32_bf16 v[70:73], v[160:163], v[234:237], v[70:73]
	v_mfma_f32_16x16x32_bf16 v[66:69], v[182:185], v[234:237], v[66:69]
	s_barrier
	s_setprio 0
	s_add_i32 s46, s48, s73
	v_lshl_add_u64 v[164:165], v[164:165], 0, s[42:43]
	s_mov_b32 m0, s46
	ds_read_b128 v[206:209], v188 offset:49152
	ds_read_b128 v[210:213], v188 offset:50176
	ds_read_b128 v[214:217], v188 offset:51200
	ds_read_b128 v[218:221], v188 offset:52224
	ds_read_b128 v[222:225], v188 offset:53248
	ds_read_b128 v[226:229], v188 offset:54272
	ds_read_b128 v[230:233], v188 offset:55296
	ds_read_b128 v[234:237], v188 offset:56320
	global_load_lds_dwordx4 v[164:165], off
	s_add_i32 m0, s46, 0x2000
	s_add_u32 s46, s60, 0x80080
	v_lshl_add_u64 v[164:165], v[242:243], 0, s[42:43]
	s_addc_u32 s47, s61, 0
	s_add_i32 s48, s49, s73
	global_load_lds_dwordx4 v[164:165], off
	v_lshl_add_u64 v[164:165], s[46:47], 0, v[166:167]
	s_mov_b32 m0, s48
	s_nop 0
	global_load_lds_dwordx4 v[164:165], off
	v_lshl_add_u64 v[164:165], s[46:47], 0, v[154:155]
	s_add_i32 m0, s48, 0x2000
	s_nop 0
	global_load_lds_dwordx4 v[164:165], off
	v_lshl_add_u64 v[164:165], v[244:245], 0, s[42:43]
	s_mov_b32 m0, s78
	s_nop 0
	global_load_lds_dwordx4 v[164:165], off
	v_lshl_add_u64 v[164:165], v[246:247], 0, s[42:43]
	s_mov_b32 m0, s79
	s_nop 0
	global_load_lds_dwordx4 v[164:165], off
	s_waitcnt vmcnt(8)
	s_waitcnt lgkmcnt(0)
	s_setprio 1
	s_waitcnt lgkmcnt(0)
	v_mfma_f32_16x16x32_bf16 v[62:65], v[130:133], v[206:209], v[62:65]
	v_mfma_f32_16x16x32_bf16 v[58:61], v[138:141], v[206:209], v[58:61]
	v_mfma_f32_16x16x32_bf16 v[50:53], v[130:133], v[214:217], v[50:53]
	v_mfma_f32_16x16x32_bf16 v[42:45], v[138:141], v[214:217], v[42:45]
	v_mfma_f32_16x16x32_bf16 v[34:37], v[130:133], v[222:225], v[34:37]
	v_mfma_f32_16x16x32_bf16 v[26:29], v[138:141], v[222:225], v[26:29]
	s_barrier
	v_mfma_f32_16x16x32_bf16 v[18:21], v[130:133], v[230:233], v[18:21]
	v_mfma_f32_16x16x32_bf16 v[10:13], v[138:141], v[230:233], v[10:13]
	v_mfma_f32_16x16x32_bf16 v[62:65], v[134:137], v[210:213], v[62:65]
	v_mfma_f32_16x16x32_bf16 v[58:61], v[142:145], v[210:213], v[58:61]
	v_mfma_f32_16x16x32_bf16 v[50:53], v[134:137], v[218:221], v[50:53]
	v_mfma_f32_16x16x32_bf16 v[42:45], v[142:145], v[218:221], v[42:45]
	v_mfma_f32_16x16x32_bf16 v[34:37], v[134:137], v[226:229], v[34:37]
	v_mfma_f32_16x16x32_bf16 v[26:29], v[142:145], v[226:229], v[26:29]
	v_mfma_f32_16x16x32_bf16 v[18:21], v[134:137], v[234:237], v[18:21]
	v_mfma_f32_16x16x32_bf16 v[10:13], v[142:145], v[234:237], v[10:13]
	v_mfma_f32_16x16x32_bf16 v[54:57], v[146:149], v[206:209], v[54:57]
	v_mfma_f32_16x16x32_bf16 v[46:49], v[178:181], v[206:209], v[46:49]
	v_mfma_f32_16x16x32_bf16 v[38:41], v[146:149], v[214:217], v[38:41]
	v_mfma_f32_16x16x32_bf16 v[30:33], v[178:181], v[214:217], v[30:33]
	v_mfma_f32_16x16x32_bf16 v[22:25], v[146:149], v[222:225], v[22:25]
	v_mfma_f32_16x16x32_bf16 v[14:17], v[178:181], v[222:225], v[14:17]
	v_mfma_f32_16x16x32_bf16 v[6:9], v[146:149], v[230:233], v[6:9]
	v_mfma_f32_16x16x32_bf16 v[2:5], v[178:181], v[230:233], v[2:5]
	v_mfma_f32_16x16x32_bf16 v[54:57], v[160:163], v[210:213], v[54:57]
	v_mfma_f32_16x16x32_bf16 v[46:49], v[182:185], v[210:213], v[46:49]
	v_mfma_f32_16x16x32_bf16 v[38:41], v[160:163], v[218:221], v[38:41]
	v_mfma_f32_16x16x32_bf16 v[30:33], v[182:185], v[218:221], v[30:33]
	v_mfma_f32_16x16x32_bf16 v[22:25], v[160:163], v[226:229], v[22:25]
	v_mfma_f32_16x16x32_bf16 v[14:17], v[182:185], v[226:229], v[14:17]
	v_mfma_f32_16x16x32_bf16 v[6:9], v[160:163], v[234:237], v[6:9]
	v_mfma_f32_16x16x32_bf16 v[2:5], v[182:185], v[234:237], v[2:5]
	s_barrier
	s_setprio 0
	s_add_i32 s84, s84, 2
	s_add_u32 s66, s66, 0x100
	s_addc_u32 s67, s67, 0
	s_add_u32 s82, s82, 0x100
	s_addc_u32 s83, s83, 0
	s_cmp_gt_u32 s84, 29
	s_cbranch_scc0 .LBB0_903
	s_and_b64 vcc, exec, s[10:11]
	s_cbranch_vccz .LBB0_906
	s_barrier

.LBB0_1035:
	s_add_u32 s46, s64, 0xfff80080
	s_addc_u32 s47, s65, -1
	s_add_i32 s48, 0, 0x10000
	s_cmp_eq_u32 s84, 28
	s_cselect_b32 s67, s17, s47
	s_cselect_b32 s66, s80, s46
	v_add_u32_e32 v140, s48, v142
	s_cselect_b32 s61, s13, s83
	s_cselect_b32 s60, s81, s82
	s_add_i32 s49, 0, 0x14000
	ds_read_b128 v[146:149], v140
	ds_read_b128 v[150:153], v140 offset:1024
	ds_read_b128 v[154:157], v140 offset:2048
	ds_read_b128 v[158:161], v140 offset:3072
	v_add_u32_e32 v140, s49, v142
	ds_read_b128 v[162:165], v140
	ds_read_b128 v[178:181], v140 offset:1024
	ds_read_b128 v[182:185], v140 offset:2048
	ds_read_b128 v[186:189], v140 offset:3072
	v_lshl_add_u64 v[140:141], s[64:65], 0, v[136:137]
	s_add_i32 m0, s23, 0xc000
	ds_read_b128 v[206:209], v144
	ds_read_b128 v[210:213], v144 offset:1024
	ds_read_b128 v[214:217], v144 offset:2048
	ds_read_b128 v[218:221], v144 offset:3072
	ds_read_b128 v[222:225], v144 offset:4096
	ds_read_b128 v[226:229], v144 offset:5120
	ds_read_b128 v[230:233], v144 offset:6144
	ds_read_b128 v[234:237], v144 offset:7168
	global_load_lds_dwordx4 v[140:141], off
	v_lshl_add_u64 v[140:141], s[64:65], 0, v[138:139]
	s_add_i32 m0, s23, 0xe000
	s_nop 0
	global_load_lds_dwordx4 v[140:141], off
	s_waitcnt vmcnt(8)
	s_waitcnt lgkmcnt(0)
	s_setprio 1
	s_waitcnt lgkmcnt(0)
	v_mfma_f32_16x16x32_bf16 v[126:129], v[146:149], v[206:209], v[126:129]
	v_mfma_f32_16x16x32_bf16 v[122:125], v[154:157], v[206:209], v[122:125]
	v_mfma_f32_16x16x32_bf16 v[110:113], v[146:149], v[214:217], v[110:113]
	v_mfma_f32_16x16x32_bf16 v[106:109], v[154:157], v[214:217], v[106:109]
	v_mfma_f32_16x16x32_bf16 v[94:97], v[146:149], v[222:225], v[94:97]
	v_mfma_f32_16x16x32_bf16 v[90:93], v[154:157], v[222:225], v[90:93]
	s_barrier
	v_mfma_f32_16x16x32_bf16 v[78:81], v[146:149], v[230:233], v[78:81]
	v_mfma_f32_16x16x32_bf16 v[74:77], v[154:157], v[230:233], v[74:77]
	v_mfma_f32_16x16x32_bf16 v[126:129], v[150:153], v[210:213], v[126:129]
	v_mfma_f32_16x16x32_bf16 v[122:125], v[158:161], v[210:213], v[122:125]
	v_mfma_f32_16x16x32_bf16 v[110:113], v[150:153], v[218:221], v[110:113]
	v_mfma_f32_16x16x32_bf16 v[106:109], v[158:161], v[218:221], v[106:109]
	v_mfma_f32_16x16x32_bf16 v[94:97], v[150:153], v[226:229], v[94:97]
	v_mfma_f32_16x16x32_bf16 v[90:93], v[158:161], v[226:229], v[90:93]
	v_mfma_f32_16x16x32_bf16 v[78:81], v[150:153], v[234:237], v[78:81]
	v_mfma_f32_16x16x32_bf16 v[74:77], v[158:161], v[234:237], v[74:77]
	v_mfma_f32_16x16x32_bf16 v[118:121], v[162:165], v[206:209], v[118:121]
	v_mfma_f32_16x16x32_bf16 v[114:117], v[182:185], v[206:209], v[114:117]
	v_mfma_f32_16x16x32_bf16 v[102:105], v[162:165], v[214:217], v[102:105]
	v_mfma_f32_16x16x32_bf16 v[98:101], v[182:185], v[214:217], v[98:101]
	v_mfma_f32_16x16x32_bf16 v[86:89], v[162:165], v[222:225], v[86:89]
	v_mfma_f32_16x16x32_bf16 v[82:85], v[182:185], v[222:225], v[82:85]
	v_mfma_f32_16x16x32_bf16 v[70:73], v[162:165], v[230:233], v[70:73]
	v_mfma_f32_16x16x32_bf16 v[66:69], v[182:185], v[230:233], v[66:69]
	v_mfma_f32_16x16x32_bf16 v[118:121], v[178:181], v[210:213], v[118:121]
	v_mfma_f32_16x16x32_bf16 v[114:117], v[186:189], v[210:213], v[114:117]
	v_mfma_f32_16x16x32_bf16 v[102:105], v[178:181], v[218:221], v[102:105]
	v_mfma_f32_16x16x32_bf16 v[98:101], v[186:189], v[218:221], v[98:101]
	v_mfma_f32_16x16x32_bf16 v[86:89], v[178:181], v[226:229], v[86:89]
	v_mfma_f32_16x16x32_bf16 v[82:85], v[186:189], v[226:229], v[82:85]
	v_mfma_f32_16x16x32_bf16 v[70:73], v[178:181], v[234:237], v[70:73]
	v_mfma_f32_16x16x32_bf16 v[66:69], v[186:189], v[234:237], v[66:69]
	s_barrier
	s_setprio 0
	s_add_i32 s46, s48, s72
	v_lshl_add_u64 v[140:141], s[60:61], 0, v[166:167]
	s_mov_b32 m0, s46
	ds_read_b128 v[206:209], v144 offset:16384
	ds_read_b128 v[210:213], v144 offset:17408
	ds_read_b128 v[214:217], v144 offset:18432
	ds_read_b128 v[218:221], v144 offset:19456
	ds_read_b128 v[222:225], v144 offset:20480
	ds_read_b128 v[226:229], v144 offset:21504
	ds_read_b128 v[230:233], v144 offset:22528
	ds_read_b128 v[234:237], v144 offset:23552
	global_load_lds_dwordx4 v[140:141], off
	s_add_i32 m0, s46, 0x2000
	s_add_u32 s46, s60, 0x80000
	v_lshl_add_u64 v[242:243], s[60:61], 0, v[134:135]
	s_addc_u32 s47, s61, 0
	s_add_i32 s48, s49, s72
	global_load_lds_dwordx4 v[242:243], off
	v_lshl_add_u64 v[244:245], s[46:47], 0, v[166:167]
	s_mov_b32 m0, s48
	v_lshl_add_u64 v[246:247], s[66:67], 0, v[132:133]
	global_load_lds_dwordx4 v[244:245], off
	v_lshl_add_u64 v[244:245], s[46:47], 0, v[134:135]
	s_add_i32 m0, s48, 0x2000
	s_nop 0
	global_load_lds_dwordx4 v[244:245], off
	v_lshl_add_u64 v[244:245], s[66:67], 0, v[130:131]
	s_mov_b32 m0, s23
	s_nop 0
	global_load_lds_dwordx4 v[244:245], off
	s_mov_b32 m0, s73
	s_nop 0
	global_load_lds_dwordx4 v[246:247], off
	s_waitcnt vmcnt(8)
	s_waitcnt lgkmcnt(0)
	s_setprio 1
	s_waitcnt lgkmcnt(0)
	v_mfma_f32_16x16x32_bf16 v[62:65], v[146:149], v[206:209], v[62:65]
	v_mfma_f32_16x16x32_bf16 v[58:61], v[154:157], v[206:209], v[58:61]
	v_mfma_f32_16x16x32_bf16 v[46:49], v[146:149], v[214:217], v[46:49]
	v_mfma_f32_16x16x32_bf16 v[42:45], v[154:157], v[214:217], v[42:45]
	v_mfma_f32_16x16x32_bf16 v[30:33], v[146:149], v[222:225], v[30:33]
	v_mfma_f32_16x16x32_bf16 v[26:29], v[154:157], v[222:225], v[26:29]
	s_barrier
	v_mfma_f32_16x16x32_bf16 v[14:17], v[146:149], v[230:233], v[14:17]
	v_mfma_f32_16x16x32_bf16 v[10:13], v[154:157], v[230:233], v[10:13]
	v_mfma_f32_16x16x32_bf16 v[62:65], v[150:153], v[210:213], v[62:65]
	v_mfma_f32_16x16x32_bf16 v[58:61], v[158:161], v[210:213], v[58:61]
	v_mfma_f32_16x16x32_bf16 v[46:49], v[150:153], v[218:221], v[46:49]
	v_mfma_f32_16x16x32_bf16 v[42:45], v[158:161], v[218:221], v[42:45]
	v_mfma_f32_16x16x32_bf16 v[30:33], v[150:153], v[226:229], v[30:33]
	v_mfma_f32_16x16x32_bf16 v[26:29], v[158:161], v[226:229], v[26:29]
	v_mfma_f32_16x16x32_bf16 v[14:17], v[150:153], v[234:237], v[14:17]
	v_mfma_f32_16x16x32_bf16 v[10:13], v[158:161], v[234:237], v[10:13]
	v_mfma_f32_16x16x32_bf16 v[54:57], v[162:165], v[206:209], v[54:57]
	v_mfma_f32_16x16x32_bf16 v[50:53], v[182:185], v[206:209], v[50:53]
	v_mfma_f32_16x16x32_bf16 v[38:41], v[162:165], v[214:217], v[38:41]
	v_mfma_f32_16x16x32_bf16 v[34:37], v[182:185], v[214:217], v[34:37]
	v_mfma_f32_16x16x32_bf16 v[22:25], v[162:165], v[222:225], v[22:25]
	v_mfma_f32_16x16x32_bf16 v[18:21], v[182:185], v[222:225], v[18:21]
	v_mfma_f32_16x16x32_bf16 v[6:9], v[162:165], v[230:233], v[6:9]
	v_mfma_f32_16x16x32_bf16 v[2:5], v[182:185], v[230:233], v[2:5]
	v_mfma_f32_16x16x32_bf16 v[54:57], v[178:181], v[210:213], v[54:57]
	v_mfma_f32_16x16x32_bf16 v[50:53], v[186:189], v[210:213], v[50:53]
	v_mfma_f32_16x16x32_bf16 v[38:41], v[178:181], v[218:221], v[38:41]
	v_mfma_f32_16x16x32_bf16 v[34:37], v[186:189], v[218:221], v[34:37]
	v_mfma_f32_16x16x32_bf16 v[22:25], v[178:181], v[226:229], v[22:25]
	v_mfma_f32_16x16x32_bf16 v[18:21], v[186:189], v[226:229], v[18:21]
	v_mfma_f32_16x16x32_bf16 v[6:9], v[178:181], v[234:237], v[6:9]
	v_mfma_f32_16x16x32_bf16 v[2:5], v[186:189], v[234:237], v[2:5]
	s_barrier
	s_setprio 0
	s_add_i32 s48, 0, 0x18000
	v_add_u32_e32 v145, s48, v142
	s_add_i32 s49, 0, 0x1c000
	ds_read_b128 v[146:149], v145
	ds_read_b128 v[150:153], v145 offset:1024
	ds_read_b128 v[154:157], v145 offset:2048
	ds_read_b128 v[158:161], v145 offset:3072
	v_add_u32_e32 v145, s49, v142
	ds_read_b128 v[162:165], v145
	ds_read_b128 v[178:181], v145 offset:1024
	ds_read_b128 v[182:185], v145 offset:2048
	ds_read_b128 v[186:189], v145 offset:3072
	s_add_u32 s46, s66, 0x80000
	s_addc_u32 s47, s67, 0
	s_mov_b32 m0, s74
	v_lshl_add_u64 v[248:249], s[46:47], 0, v[130:131]
	ds_read_b128 v[206:209], v144 offset:32768
	ds_read_b128 v[210:213], v144 offset:33792
	ds_read_b128 v[214:217], v144 offset:34816
	ds_read_b128 v[218:221], v144 offset:35840
	ds_read_b128 v[222:225], v144 offset:36864
	ds_read_b128 v[226:229], v144 offset:37888
	ds_read_b128 v[230:233], v144 offset:38912
	ds_read_b128 v[234:237], v144 offset:39936
	global_load_lds_dwordx4 v[248:249], off
	v_lshl_add_u64 v[248:249], s[46:47], 0, v[132:133]
	s_mov_b32 m0, s75
	s_nop 0
	global_load_lds_dwordx4 v[248:249], off
	s_waitcnt vmcnt(8)
	s_waitcnt lgkmcnt(0)
	s_setprio 1
	s_waitcnt lgkmcnt(0)
	v_mfma_f32_16x16x32_bf16 v[126:129], v[146:149], v[206:209], v[126:129]
	v_mfma_f32_16x16x32_bf16 v[122:125], v[154:157], v[206:209], v[122:125]
	v_mfma_f32_16x16x32_bf16 v[110:113], v[146:149], v[214:217], v[110:113]
	v_mfma_f32_16x16x32_bf16 v[106:109], v[154:157], v[214:217], v[106:109]
	v_mfma_f32_16x16x32_bf16 v[94:97], v[146:149], v[222:225], v[94:97]
	v_mfma_f32_16x16x32_bf16 v[90:93], v[154:157], v[222:225], v[90:93]
	s_barrier
	v_mfma_f32_16x16x32_bf16 v[78:81], v[146:149], v[230:233], v[78:81]
	v_mfma_f32_16x16x32_bf16 v[74:77], v[154:157], v[230:233], v[74:77]
	v_mfma_f32_16x16x32_bf16 v[126:129], v[150:153], v[210:213], v[126:129]
	v_mfma_f32_16x16x32_bf16 v[122:125], v[158:161], v[210:213], v[122:125]
	v_mfma_f32_16x16x32_bf16 v[110:113], v[150:153], v[218:221], v[110:113]
	v_mfma_f32_16x16x32_bf16 v[106:109], v[158:161], v[218:221], v[106:109]
	v_mfma_f32_16x16x32_bf16 v[94:97], v[150:153], v[226:229], v[94:97]
	v_mfma_f32_16x16x32_bf16 v[90:93], v[158:161], v[226:229], v[90:93]
	v_mfma_f32_16x16x32_bf16 v[78:81], v[150:153], v[234:237], v[78:81]
	v_mfma_f32_16x16x32_bf16 v[74:77], v[158:161], v[234:237], v[74:77]
	v_mfma_f32_16x16x32_bf16 v[118:121], v[162:165], v[206:209], v[118:121]
	v_mfma_f32_16x16x32_bf16 v[114:117], v[182:185], v[206:209], v[114:117]
	v_mfma_f32_16x16x32_bf16 v[102:105], v[162:165], v[214:217], v[102:105]
	v_mfma_f32_16x16x32_bf16 v[98:101], v[182:185], v[214:217], v[98:101]
	v_mfma_f32_16x16x32_bf16 v[86:89], v[162:165], v[222:225], v[86:89]
	v_mfma_f32_16x16x32_bf16 v[82:85], v[182:185], v[222:225], v[82:85]
	v_mfma_f32_16x16x32_bf16 v[70:73], v[162:165], v[230:233], v[70:73]
	v_mfma_f32_16x16x32_bf16 v[66:69], v[182:185], v[230:233], v[66:69]
	v_mfma_f32_16x16x32_bf16 v[118:121], v[178:181], v[210:213], v[118:121]
	v_mfma_f32_16x16x32_bf16 v[114:117], v[186:189], v[210:213], v[114:117]
	v_mfma_f32_16x16x32_bf16 v[102:105], v[178:181], v[218:221], v[102:105]
	v_mfma_f32_16x16x32_bf16 v[98:101], v[186:189], v[218:221], v[98:101]
	v_mfma_f32_16x16x32_bf16 v[86:89], v[178:181], v[226:229], v[86:89]
	v_mfma_f32_16x16x32_bf16 v[82:85], v[186:189], v[226:229], v[82:85]
	v_mfma_f32_16x16x32_bf16 v[70:73], v[178:181], v[234:237], v[70:73]
	v_mfma_f32_16x16x32_bf16 v[66:69], v[186:189], v[234:237], v[66:69]
	s_barrier
	s_setprio 0
	s_add_i32 s46, s48, s72
	v_lshl_add_u64 v[140:141], v[140:141], 0, s[42:43]
	s_mov_b32 m0, s46
	ds_read_b128 v[206:209], v144 offset:49152
	ds_read_b128 v[210:213], v144 offset:50176
	ds_read_b128 v[214:217], v144 offset:51200
	ds_read_b128 v[218:221], v144 offset:52224
	ds_read_b128 v[222:225], v144 offset:53248
	ds_read_b128 v[226:229], v144 offset:54272
	ds_read_b128 v[230:233], v144 offset:55296
	ds_read_b128 v[234:237], v144 offset:56320
	global_load_lds_dwordx4 v[140:141], off
	s_add_i32 m0, s46, 0x2000
	s_add_u32 s46, s60, 0x80080
	v_lshl_add_u64 v[140:141], v[242:243], 0, s[42:43]
	s_addc_u32 s47, s61, 0
	s_add_i32 s48, s49, s72
	global_load_lds_dwordx4 v[140:141], off
	v_lshl_add_u64 v[140:141], s[46:47], 0, v[166:167]
	s_mov_b32 m0, s48
	s_nop 0
	global_load_lds_dwordx4 v[140:141], off
	v_lshl_add_u64 v[140:141], s[46:47], 0, v[134:135]
	s_add_i32 m0, s48, 0x2000
	s_nop 0
	global_load_lds_dwordx4 v[140:141], off
	v_lshl_add_u64 v[140:141], v[244:245], 0, s[42:43]
	s_mov_b32 m0, s76
	s_nop 0
	global_load_lds_dwordx4 v[140:141], off
	v_lshl_add_u64 v[140:141], v[246:247], 0, s[42:43]
	s_mov_b32 m0, s77
	s_nop 0
	global_load_lds_dwordx4 v[140:141], off
	s_waitcnt vmcnt(8)
	s_waitcnt lgkmcnt(0)
	s_setprio 1
	s_waitcnt lgkmcnt(0)
	v_mfma_f32_16x16x32_bf16 v[62:65], v[146:149], v[206:209], v[62:65]
	v_mfma_f32_16x16x32_bf16 v[58:61], v[154:157], v[206:209], v[58:61]
	v_mfma_f32_16x16x32_bf16 v[46:49], v[146:149], v[214:217], v[46:49]
	v_mfma_f32_16x16x32_bf16 v[42:45], v[154:157], v[214:217], v[42:45]
	v_mfma_f32_16x16x32_bf16 v[30:33], v[146:149], v[222:225], v[30:33]
	v_mfma_f32_16x16x32_bf16 v[26:29], v[154:157], v[222:225], v[26:29]
	s_barrier
	v_mfma_f32_16x16x32_bf16 v[14:17], v[146:149], v[230:233], v[14:17]
	v_mfma_f32_16x16x32_bf16 v[10:13], v[154:157], v[230:233], v[10:13]
	v_mfma_f32_16x16x32_bf16 v[62:65], v[150:153], v[210:213], v[62:65]
	v_mfma_f32_16x16x32_bf16 v[58:61], v[158:161], v[210:213], v[58:61]
	v_mfma_f32_16x16x32_bf16 v[46:49], v[150:153], v[218:221], v[46:49]
	v_mfma_f32_16x16x32_bf16 v[42:45], v[158:161], v[218:221], v[42:45]
	v_mfma_f32_16x16x32_bf16 v[30:33], v[150:153], v[226:229], v[30:33]
	v_mfma_f32_16x16x32_bf16 v[26:29], v[158:161], v[226:229], v[26:29]
	v_mfma_f32_16x16x32_bf16 v[14:17], v[150:153], v[234:237], v[14:17]
	v_mfma_f32_16x16x32_bf16 v[10:13], v[158:161], v[234:237], v[10:13]
	v_mfma_f32_16x16x32_bf16 v[54:57], v[162:165], v[206:209], v[54:57]
	v_mfma_f32_16x16x32_bf16 v[50:53], v[182:185], v[206:209], v[50:53]
	v_mfma_f32_16x16x32_bf16 v[38:41], v[162:165], v[214:217], v[38:41]
	v_mfma_f32_16x16x32_bf16 v[34:37], v[182:185], v[214:217], v[34:37]
	v_mfma_f32_16x16x32_bf16 v[22:25], v[162:165], v[222:225], v[22:25]
	v_mfma_f32_16x16x32_bf16 v[18:21], v[182:185], v[222:225], v[18:21]
	v_mfma_f32_16x16x32_bf16 v[6:9], v[162:165], v[230:233], v[6:9]
	v_mfma_f32_16x16x32_bf16 v[2:5], v[182:185], v[230:233], v[2:5]
	v_mfma_f32_16x16x32_bf16 v[54:57], v[178:181], v[210:213], v[54:57]
	v_mfma_f32_16x16x32_bf16 v[50:53], v[186:189], v[210:213], v[50:53]
	v_mfma_f32_16x16x32_bf16 v[38:41], v[178:181], v[218:221], v[38:41]
	v_mfma_f32_16x16x32_bf16 v[34:37], v[186:189], v[218:221], v[34:37]
	v_mfma_f32_16x16x32_bf16 v[22:25], v[178:181], v[226:229], v[22:25]
	v_mfma_f32_16x16x32_bf16 v[18:21], v[186:189], v[226:229], v[18:21]
	v_mfma_f32_16x16x32_bf16 v[6:9], v[178:181], v[234:237], v[6:9]
	v_mfma_f32_16x16x32_bf16 v[2:5], v[186:189], v[234:237], v[2:5]
	s_barrier
	s_setprio 0
	s_add_i32 s84, s84, 2
	s_add_u32 s64, s64, 0x100
	s_addc_u32 s65, s65, 0
	s_add_u32 s82, s82, 0x100
	s_addc_u32 s83, s83, 0
	s_cmp_gt_u32 s84, 29
	s_cbranch_scc0 .LBB0_1035
	s_and_b64 vcc, exec, s[10:11]
	s_cbranch_vccz .LBB0_1038
	s_barrier

.LBB0_1112:
	s_add_u32 s46, s64, 0xffe00080
	s_addc_u32 s47, s65, -1
	s_add_i32 s48, 0, 0x10000
	s_cmpk_eq_i32 s84, 0x7c
	s_cselect_b32 s67, s19, s47
	s_cselect_b32 s66, s80, s46
	s_cselect_b32 s61, s17, s83
	s_cselect_b32 s60, s81, s82
	s_add_i32 s49, 0, 0x14000
	v_add_u32_e32 v142, s48, v182
	v_add_u32_e32 v164, s49, v182
	ds_read_b128 v[130:133], v142
	ds_read_b128 v[134:137], v142 offset:1024
	ds_read_b128 v[138:141], v142 offset:2048
	ds_read_b128 v[142:145], v142 offset:3072
	ds_read_b128 v[146:149], v164
	ds_read_b128 v[160:163], v164 offset:1024
	ds_read_b128 v[178:181], v164 offset:2048
	ds_read_b128 v[186:189], v164 offset:3072
	v_lshl_add_u64 v[164:165], s[64:65], 0, v[156:157]
	s_add_i32 m0, s63, 0xc000
	ds_read_b128 v[206:209], v184
	ds_read_b128 v[210:213], v184 offset:1024
	ds_read_b128 v[214:217], v184 offset:2048
	ds_read_b128 v[218:221], v184 offset:3072
	ds_read_b128 v[222:225], v184 offset:4096
	ds_read_b128 v[226:229], v184 offset:5120
	ds_read_b128 v[230:233], v184 offset:6144
	ds_read_b128 v[234:237], v184 offset:7168
	global_load_lds_dwordx4 v[164:165], off
	v_lshl_add_u64 v[164:165], s[64:65], 0, v[158:159]
	s_add_i32 m0, s63, 0xe000
	s_nop 0
	global_load_lds_dwordx4 v[164:165], off
	s_waitcnt vmcnt(8)
	s_waitcnt lgkmcnt(0)
	s_setprio 1
	s_waitcnt lgkmcnt(0)
	v_mfma_f32_16x16x32_bf16 v[126:129], v[130:133], v[206:209], v[126:129]
	v_mfma_f32_16x16x32_bf16 v[122:125], v[138:141], v[206:209], v[122:125]
	v_mfma_f32_16x16x32_bf16 v[118:121], v[130:133], v[214:217], v[118:121]
	v_mfma_f32_16x16x32_bf16 v[114:117], v[138:141], v[214:217], v[114:117]
	v_mfma_f32_16x16x32_bf16 v[94:97], v[130:133], v[222:225], v[94:97]
	v_mfma_f32_16x16x32_bf16 v[90:93], v[138:141], v[222:225], v[90:93]
	s_barrier
	v_mfma_f32_16x16x32_bf16 v[82:85], v[130:133], v[230:233], v[82:85]
	v_mfma_f32_16x16x32_bf16 v[74:77], v[138:141], v[230:233], v[74:77]
	v_mfma_f32_16x16x32_bf16 v[126:129], v[134:137], v[210:213], v[126:129]
	v_mfma_f32_16x16x32_bf16 v[122:125], v[142:145], v[210:213], v[122:125]
	v_mfma_f32_16x16x32_bf16 v[118:121], v[134:137], v[218:221], v[118:121]
	v_mfma_f32_16x16x32_bf16 v[114:117], v[142:145], v[218:221], v[114:117]
	v_mfma_f32_16x16x32_bf16 v[94:97], v[134:137], v[226:229], v[94:97]
	v_mfma_f32_16x16x32_bf16 v[90:93], v[142:145], v[226:229], v[90:93]
	v_mfma_f32_16x16x32_bf16 v[82:85], v[134:137], v[234:237], v[82:85]
	v_mfma_f32_16x16x32_bf16 v[74:77], v[142:145], v[234:237], v[74:77]
	v_mfma_f32_16x16x32_bf16 v[110:113], v[146:149], v[206:209], v[110:113]
	v_mfma_f32_16x16x32_bf16 v[106:109], v[178:181], v[206:209], v[106:109]
	v_mfma_f32_16x16x32_bf16 v[102:105], v[146:149], v[214:217], v[102:105]
	v_mfma_f32_16x16x32_bf16 v[98:101], v[178:181], v[214:217], v[98:101]
	v_mfma_f32_16x16x32_bf16 v[86:89], v[146:149], v[222:225], v[86:89]
	v_mfma_f32_16x16x32_bf16 v[78:81], v[178:181], v[222:225], v[78:81]
	v_mfma_f32_16x16x32_bf16 v[70:73], v[146:149], v[230:233], v[70:73]
	v_mfma_f32_16x16x32_bf16 v[66:69], v[178:181], v[230:233], v[66:69]
	v_mfma_f32_16x16x32_bf16 v[110:113], v[160:163], v[210:213], v[110:113]
	v_mfma_f32_16x16x32_bf16 v[106:109], v[186:189], v[210:213], v[106:109]
	v_mfma_f32_16x16x32_bf16 v[102:105], v[160:163], v[218:221], v[102:105]
	v_mfma_f32_16x16x32_bf16 v[98:101], v[186:189], v[218:221], v[98:101]
	v_mfma_f32_16x16x32_bf16 v[86:89], v[160:163], v[226:229], v[86:89]
	v_mfma_f32_16x16x32_bf16 v[78:81], v[186:189], v[226:229], v[78:81]
	v_mfma_f32_16x16x32_bf16 v[70:73], v[160:163], v[234:237], v[70:73]
	v_mfma_f32_16x16x32_bf16 v[66:69], v[186:189], v[234:237], v[66:69]
	s_barrier
	s_setprio 0
	s_add_i32 s46, s48, s72
	v_lshl_add_u64 v[164:165], s[60:61], 0, v[166:167]
	s_mov_b32 m0, s46
	ds_read_b128 v[206:209], v184 offset:16384
	ds_read_b128 v[210:213], v184 offset:17408
	ds_read_b128 v[214:217], v184 offset:18432
	ds_read_b128 v[218:221], v184 offset:19456
	ds_read_b128 v[222:225], v184 offset:20480
	ds_read_b128 v[226:229], v184 offset:21504
	ds_read_b128 v[230:233], v184 offset:22528
	ds_read_b128 v[234:237], v184 offset:23552
	global_load_lds_dwordx4 v[164:165], off
	s_add_i32 m0, s46, 0x2000
	s_add_u32 s46, s60, 0x200000
	v_lshl_add_u64 v[242:243], s[60:61], 0, v[154:155]
	s_addc_u32 s47, s61, 0
	s_add_i32 s48, s49, s72
	global_load_lds_dwordx4 v[242:243], off
	v_lshl_add_u64 v[244:245], s[46:47], 0, v[166:167]
	s_mov_b32 m0, s48
	v_lshl_add_u64 v[246:247], s[66:67], 0, v[152:153]
	global_load_lds_dwordx4 v[244:245], off
	v_lshl_add_u64 v[244:245], s[46:47], 0, v[154:155]
	s_add_i32 m0, s48, 0x2000
	s_nop 0
	global_load_lds_dwordx4 v[244:245], off
	v_lshl_add_u64 v[244:245], s[66:67], 0, v[150:151]
	s_mov_b32 m0, s63
	s_nop 0
	global_load_lds_dwordx4 v[244:245], off
	s_mov_b32 m0, s73
	s_nop 0
	global_load_lds_dwordx4 v[246:247], off
	s_waitcnt vmcnt(8)
	s_waitcnt lgkmcnt(0)
	s_setprio 1
	s_waitcnt lgkmcnt(0)
	v_mfma_f32_16x16x32_bf16 v[62:65], v[130:133], v[206:209], v[62:65]
	v_mfma_f32_16x16x32_bf16 v[58:61], v[138:141], v[206:209], v[58:61]
	v_mfma_f32_16x16x32_bf16 v[50:53], v[130:133], v[214:217], v[50:53]
	v_mfma_f32_16x16x32_bf16 v[42:45], v[138:141], v[214:217], v[42:45]
	v_mfma_f32_16x16x32_bf16 v[34:37], v[130:133], v[222:225], v[34:37]
	v_mfma_f32_16x16x32_bf16 v[26:29], v[138:141], v[222:225], v[26:29]
	s_barrier
	v_mfma_f32_16x16x32_bf16 v[18:21], v[130:133], v[230:233], v[18:21]
	v_mfma_f32_16x16x32_bf16 v[10:13], v[138:141], v[230:233], v[10:13]
	v_mfma_f32_16x16x32_bf16 v[62:65], v[134:137], v[210:213], v[62:65]
	v_mfma_f32_16x16x32_bf16 v[58:61], v[142:145], v[210:213], v[58:61]
	v_mfma_f32_16x16x32_bf16 v[50:53], v[134:137], v[218:221], v[50:53]
	v_mfma_f32_16x16x32_bf16 v[42:45], v[142:145], v[218:221], v[42:45]
	v_mfma_f32_16x16x32_bf16 v[34:37], v[134:137], v[226:229], v[34:37]
	v_mfma_f32_16x16x32_bf16 v[26:29], v[142:145], v[226:229], v[26:29]
	v_mfma_f32_16x16x32_bf16 v[18:21], v[134:137], v[234:237], v[18:21]
	v_mfma_f32_16x16x32_bf16 v[10:13], v[142:145], v[234:237], v[10:13]
	v_mfma_f32_16x16x32_bf16 v[54:57], v[146:149], v[206:209], v[54:57]
	v_mfma_f32_16x16x32_bf16 v[46:49], v[178:181], v[206:209], v[46:49]
	v_mfma_f32_16x16x32_bf16 v[38:41], v[146:149], v[214:217], v[38:41]
	v_mfma_f32_16x16x32_bf16 v[30:33], v[178:181], v[214:217], v[30:33]
	v_mfma_f32_16x16x32_bf16 v[22:25], v[146:149], v[222:225], v[22:25]
	v_mfma_f32_16x16x32_bf16 v[14:17], v[178:181], v[222:225], v[14:17]
	v_mfma_f32_16x16x32_bf16 v[6:9], v[146:149], v[230:233], v[6:9]
	v_mfma_f32_16x16x32_bf16 v[2:5], v[178:181], v[230:233], v[2:5]
	v_mfma_f32_16x16x32_bf16 v[54:57], v[160:163], v[210:213], v[54:57]
	v_mfma_f32_16x16x32_bf16 v[46:49], v[186:189], v[210:213], v[46:49]
	v_mfma_f32_16x16x32_bf16 v[38:41], v[160:163], v[218:221], v[38:41]
	v_mfma_f32_16x16x32_bf16 v[30:33], v[186:189], v[218:221], v[30:33]
	v_mfma_f32_16x16x32_bf16 v[22:25], v[160:163], v[226:229], v[22:25]
	v_mfma_f32_16x16x32_bf16 v[14:17], v[186:189], v[226:229], v[14:17]
	v_mfma_f32_16x16x32_bf16 v[6:9], v[160:163], v[234:237], v[6:9]
	v_mfma_f32_16x16x32_bf16 v[2:5], v[186:189], v[234:237], v[2:5]
	s_barrier
	s_setprio 0
	s_add_i32 s48, 0, 0x18000
	s_add_i32 s49, 0, 0x1c000
	v_add_u32_e32 v142, s48, v182
	v_add_u32_e32 v185, s49, v182
	ds_read_b128 v[130:133], v142
	ds_read_b128 v[134:137], v142 offset:1024
	ds_read_b128 v[138:141], v142 offset:2048
	ds_read_b128 v[142:145], v142 offset:3072
	ds_read_b128 v[146:149], v185
	ds_read_b128 v[160:163], v185 offset:1024
	ds_read_b128 v[178:181], v185 offset:2048
	ds_read_b128 v[186:189], v185 offset:3072
	s_add_u32 s46, s66, 0x200000
	s_addc_u32 s47, s67, 0
	s_mov_b32 m0, s74
	v_lshl_add_u64 v[248:249], s[46:47], 0, v[150:151]
	ds_read_b128 v[206:209], v184 offset:32768
	ds_read_b128 v[210:213], v184 offset:33792
	ds_read_b128 v[214:217], v184 offset:34816
	ds_read_b128 v[218:221], v184 offset:35840
	ds_read_b128 v[222:225], v184 offset:36864
	ds_read_b128 v[226:229], v184 offset:37888
	ds_read_b128 v[230:233], v184 offset:38912
	ds_read_b128 v[234:237], v184 offset:39936
	global_load_lds_dwordx4 v[248:249], off
	v_lshl_add_u64 v[248:249], s[46:47], 0, v[152:153]
	s_mov_b32 m0, s75
	s_nop 0
	global_load_lds_dwordx4 v[248:249], off
	s_waitcnt vmcnt(8)
	s_waitcnt lgkmcnt(0)
	s_setprio 1
	s_waitcnt lgkmcnt(0)
	v_mfma_f32_16x16x32_bf16 v[126:129], v[130:133], v[206:209], v[126:129]
	v_mfma_f32_16x16x32_bf16 v[122:125], v[138:141], v[206:209], v[122:125]
	v_mfma_f32_16x16x32_bf16 v[118:121], v[130:133], v[214:217], v[118:121]
	v_mfma_f32_16x16x32_bf16 v[114:117], v[138:141], v[214:217], v[114:117]
	v_mfma_f32_16x16x32_bf16 v[94:97], v[130:133], v[222:225], v[94:97]
	v_mfma_f32_16x16x32_bf16 v[90:93], v[138:141], v[222:225], v[90:93]
	s_barrier
	v_mfma_f32_16x16x32_bf16 v[82:85], v[130:133], v[230:233], v[82:85]
	v_mfma_f32_16x16x32_bf16 v[74:77], v[138:141], v[230:233], v[74:77]
	v_mfma_f32_16x16x32_bf16 v[126:129], v[134:137], v[210:213], v[126:129]
	v_mfma_f32_16x16x32_bf16 v[122:125], v[142:145], v[210:213], v[122:125]
	v_mfma_f32_16x16x32_bf16 v[118:121], v[134:137], v[218:221], v[118:121]
	v_mfma_f32_16x16x32_bf16 v[114:117], v[142:145], v[218:221], v[114:117]
	v_mfma_f32_16x16x32_bf16 v[94:97], v[134:137], v[226:229], v[94:97]
	v_mfma_f32_16x16x32_bf16 v[90:93], v[142:145], v[226:229], v[90:93]
	v_mfma_f32_16x16x32_bf16 v[82:85], v[134:137], v[234:237], v[82:85]
	v_mfma_f32_16x16x32_bf16 v[74:77], v[142:145], v[234:237], v[74:77]
	v_mfma_f32_16x16x32_bf16 v[110:113], v[146:149], v[206:209], v[110:113]
	v_mfma_f32_16x16x32_bf16 v[106:109], v[178:181], v[206:209], v[106:109]
	v_mfma_f32_16x16x32_bf16 v[102:105], v[146:149], v[214:217], v[102:105]
	v_mfma_f32_16x16x32_bf16 v[98:101], v[178:181], v[214:217], v[98:101]
	v_mfma_f32_16x16x32_bf16 v[86:89], v[146:149], v[222:225], v[86:89]
	v_mfma_f32_16x16x32_bf16 v[78:81], v[178:181], v[222:225], v[78:81]
	v_mfma_f32_16x16x32_bf16 v[70:73], v[146:149], v[230:233], v[70:73]
	v_mfma_f32_16x16x32_bf16 v[66:69], v[178:181], v[230:233], v[66:69]
	v_mfma_f32_16x16x32_bf16 v[110:113], v[160:163], v[210:213], v[110:113]
	v_mfma_f32_16x16x32_bf16 v[106:109], v[186:189], v[210:213], v[106:109]
	v_mfma_f32_16x16x32_bf16 v[102:105], v[160:163], v[218:221], v[102:105]
	v_mfma_f32_16x16x32_bf16 v[98:101], v[186:189], v[218:221], v[98:101]
	v_mfma_f32_16x16x32_bf16 v[86:89], v[160:163], v[226:229], v[86:89]
	v_mfma_f32_16x16x32_bf16 v[78:81], v[186:189], v[226:229], v[78:81]
	v_mfma_f32_16x16x32_bf16 v[70:73], v[160:163], v[234:237], v[70:73]
	v_mfma_f32_16x16x32_bf16 v[66:69], v[186:189], v[234:237], v[66:69]
	s_barrier
	s_setprio 0
	s_add_i32 s46, s48, s72
	v_lshl_add_u64 v[164:165], v[164:165], 0, s[42:43]
	s_mov_b32 m0, s46
	ds_read_b128 v[206:209], v184 offset:49152
	ds_read_b128 v[210:213], v184 offset:50176
	ds_read_b128 v[214:217], v184 offset:51200
	ds_read_b128 v[218:221], v184 offset:52224
	ds_read_b128 v[222:225], v184 offset:53248
	ds_read_b128 v[226:229], v184 offset:54272
	ds_read_b128 v[230:233], v184 offset:55296
	ds_read_b128 v[234:237], v184 offset:56320
	global_load_lds_dwordx4 v[164:165], off
	s_add_i32 m0, s46, 0x2000
	s_add_u32 s46, s60, 0x200080
	v_lshl_add_u64 v[164:165], v[242:243], 0, s[42:43]
	s_addc_u32 s47, s61, 0
	s_add_i32 s48, s49, s72
	global_load_lds_dwordx4 v[164:165], off
	v_lshl_add_u64 v[164:165], s[46:47], 0, v[166:167]
	s_mov_b32 m0, s48
	s_nop 0
	global_load_lds_dwordx4 v[164:165], off
	v_lshl_add_u64 v[164:165], s[46:47], 0, v[154:155]
	s_add_i32 m0, s48, 0x2000
	s_nop 0
	global_load_lds_dwordx4 v[164:165], off
	v_lshl_add_u64 v[164:165], v[244:245], 0, s[42:43]
	s_mov_b32 m0, s76
	s_nop 0
	global_load_lds_dwordx4 v[164:165], off
	v_lshl_add_u64 v[164:165], v[246:247], 0, s[42:43]
	s_mov_b32 m0, s77
	s_nop 0
	global_load_lds_dwordx4 v[164:165], off
	s_waitcnt vmcnt(8)
	s_waitcnt lgkmcnt(0)
	s_setprio 1
	s_waitcnt lgkmcnt(0)
	v_mfma_f32_16x16x32_bf16 v[62:65], v[130:133], v[206:209], v[62:65]
	v_mfma_f32_16x16x32_bf16 v[58:61], v[138:141], v[206:209], v[58:61]
	v_mfma_f32_16x16x32_bf16 v[50:53], v[130:133], v[214:217], v[50:53]
	v_mfma_f32_16x16x32_bf16 v[42:45], v[138:141], v[214:217], v[42:45]
	v_mfma_f32_16x16x32_bf16 v[34:37], v[130:133], v[222:225], v[34:37]
	v_mfma_f32_16x16x32_bf16 v[26:29], v[138:141], v[222:225], v[26:29]
	s_barrier
	v_mfma_f32_16x16x32_bf16 v[18:21], v[130:133], v[230:233], v[18:21]
	v_mfma_f32_16x16x32_bf16 v[10:13], v[138:141], v[230:233], v[10:13]
	v_mfma_f32_16x16x32_bf16 v[62:65], v[134:137], v[210:213], v[62:65]
	v_mfma_f32_16x16x32_bf16 v[58:61], v[142:145], v[210:213], v[58:61]
	v_mfma_f32_16x16x32_bf16 v[50:53], v[134:137], v[218:221], v[50:53]
	v_mfma_f32_16x16x32_bf16 v[42:45], v[142:145], v[218:221], v[42:45]
	v_mfma_f32_16x16x32_bf16 v[34:37], v[134:137], v[226:229], v[34:37]
	v_mfma_f32_16x16x32_bf16 v[26:29], v[142:145], v[226:229], v[26:29]
	v_mfma_f32_16x16x32_bf16 v[18:21], v[134:137], v[234:237], v[18:21]
	v_mfma_f32_16x16x32_bf16 v[10:13], v[142:145], v[234:237], v[10:13]
	v_mfma_f32_16x16x32_bf16 v[54:57], v[146:149], v[206:209], v[54:57]
	v_mfma_f32_16x16x32_bf16 v[46:49], v[178:181], v[206:209], v[46:49]
	v_mfma_f32_16x16x32_bf16 v[38:41], v[146:149], v[214:217], v[38:41]
	v_mfma_f32_16x16x32_bf16 v[30:33], v[178:181], v[214:217], v[30:33]
	v_mfma_f32_16x16x32_bf16 v[22:25], v[146:149], v[222:225], v[22:25]
	v_mfma_f32_16x16x32_bf16 v[14:17], v[178:181], v[222:225], v[14:17]
	v_mfma_f32_16x16x32_bf16 v[6:9], v[146:149], v[230:233], v[6:9]
	v_mfma_f32_16x16x32_bf16 v[2:5], v[178:181], v[230:233], v[2:5]
	v_mfma_f32_16x16x32_bf16 v[54:57], v[160:163], v[210:213], v[54:57]
	v_mfma_f32_16x16x32_bf16 v[46:49], v[186:189], v[210:213], v[46:49]
	v_mfma_f32_16x16x32_bf16 v[38:41], v[160:163], v[218:221], v[38:41]
	v_mfma_f32_16x16x32_bf16 v[30:33], v[186:189], v[218:221], v[30:33]
	v_mfma_f32_16x16x32_bf16 v[22:25], v[160:163], v[226:229], v[22:25]
	v_mfma_f32_16x16x32_bf16 v[14:17], v[186:189], v[226:229], v[14:17]
	v_mfma_f32_16x16x32_bf16 v[6:9], v[160:163], v[234:237], v[6:9]
	v_mfma_f32_16x16x32_bf16 v[2:5], v[186:189], v[234:237], v[2:5]
	s_barrier
	s_setprio 0
	s_add_i32 s84, s84, 2
	s_add_u32 s64, s64, 0x100
	s_addc_u32 s65, s65, 0
	s_add_u32 s82, s82, 0x100
	s_addc_u32 s83, s83, 0
	s_cmpk_gt_u32 s84, 0x7d
	s_cbranch_scc0 .LBB0_1112
	s_and_b64 vcc, exec, s[12:13]
	s_cbranch_vccz .LBB0_1115
	s_barrier

.LBB0_1138:
	s_add_u32 s46, s62, 0xffe00080
	s_addc_u32 s47, s63, -1
	s_add_i32 s48, 0, 0x10000
	s_cmpk_eq_i32 s82, 0x7c
	s_cselect_b32 s65, s17, s47
	s_cselect_b32 s64, s78, s46
	s_cselect_b32 s61, s13, s81
	s_cselect_b32 s60, s79, s80
	s_add_i32 s49, 0, 0x14000
	v_add_u32_e32 v142, s48, v186
	v_add_u32_e32 v164, s49, v186
	ds_read_b128 v[130:133], v142
	ds_read_b128 v[134:137], v142 offset:1024
	ds_read_b128 v[138:141], v142 offset:2048
	ds_read_b128 v[142:145], v142 offset:3072
	ds_read_b128 v[146:149], v164
	ds_read_b128 v[160:163], v164 offset:1024
	ds_read_b128 v[178:181], v164 offset:2048
	ds_read_b128 v[182:185], v164 offset:3072
	v_lshl_add_u64 v[164:165], s[62:63], 0, v[156:157]
	s_add_i32 m0, s71, 0xc000
	ds_read_b128 v[206:209], v188
	ds_read_b128 v[210:213], v188 offset:1024
	ds_read_b128 v[214:217], v188 offset:2048
	ds_read_b128 v[218:221], v188 offset:3072
	ds_read_b128 v[222:225], v188 offset:4096
	ds_read_b128 v[226:229], v188 offset:5120
	ds_read_b128 v[230:233], v188 offset:6144
	ds_read_b128 v[234:237], v188 offset:7168
	global_load_lds_dwordx4 v[164:165], off
	v_lshl_add_u64 v[164:165], s[62:63], 0, v[158:159]
	s_add_i32 m0, s71, 0xe000
	s_nop 0
	global_load_lds_dwordx4 v[164:165], off
	s_waitcnt vmcnt(8)
	s_waitcnt lgkmcnt(0)
	s_setprio 1
	s_waitcnt lgkmcnt(0)
	v_mfma_f32_16x16x32_bf16 v[126:129], v[130:133], v[206:209], v[126:129]
	v_mfma_f32_16x16x32_bf16 v[122:125], v[138:141], v[206:209], v[122:125]
	v_mfma_f32_16x16x32_bf16 v[118:121], v[130:133], v[214:217], v[118:121]
	v_mfma_f32_16x16x32_bf16 v[110:113], v[138:141], v[214:217], v[110:113]
	v_mfma_f32_16x16x32_bf16 v[94:97], v[130:133], v[222:225], v[94:97]
	v_mfma_f32_16x16x32_bf16 v[90:93], v[138:141], v[222:225], v[90:93]
	s_barrier
	v_mfma_f32_16x16x32_bf16 v[82:85], v[130:133], v[230:233], v[82:85]
	v_mfma_f32_16x16x32_bf16 v[74:77], v[138:141], v[230:233], v[74:77]
	v_mfma_f32_16x16x32_bf16 v[126:129], v[134:137], v[210:213], v[126:129]
	v_mfma_f32_16x16x32_bf16 v[122:125], v[142:145], v[210:213], v[122:125]
	v_mfma_f32_16x16x32_bf16 v[118:121], v[134:137], v[218:221], v[118:121]
	v_mfma_f32_16x16x32_bf16 v[110:113], v[142:145], v[218:221], v[110:113]
	v_mfma_f32_16x16x32_bf16 v[94:97], v[134:137], v[226:229], v[94:97]
	v_mfma_f32_16x16x32_bf16 v[90:93], v[142:145], v[226:229], v[90:93]
	v_mfma_f32_16x16x32_bf16 v[82:85], v[134:137], v[234:237], v[82:85]
	v_mfma_f32_16x16x32_bf16 v[74:77], v[142:145], v[234:237], v[74:77]
	v_mfma_f32_16x16x32_bf16 v[114:117], v[146:149], v[206:209], v[114:117]
	v_mfma_f32_16x16x32_bf16 v[106:109], v[178:181], v[206:209], v[106:109]
	v_mfma_f32_16x16x32_bf16 v[102:105], v[146:149], v[214:217], v[102:105]
	v_mfma_f32_16x16x32_bf16 v[98:101], v[178:181], v[214:217], v[98:101]
	v_mfma_f32_16x16x32_bf16 v[86:89], v[146:149], v[222:225], v[86:89]
	v_mfma_f32_16x16x32_bf16 v[78:81], v[178:181], v[222:225], v[78:81]
	v_mfma_f32_16x16x32_bf16 v[70:73], v[146:149], v[230:233], v[70:73]
	v_mfma_f32_16x16x32_bf16 v[66:69], v[178:181], v[230:233], v[66:69]
	v_mfma_f32_16x16x32_bf16 v[114:117], v[160:163], v[210:213], v[114:117]
	v_mfma_f32_16x16x32_bf16 v[106:109], v[182:185], v[210:213], v[106:109]
	v_mfma_f32_16x16x32_bf16 v[102:105], v[160:163], v[218:221], v[102:105]
	v_mfma_f32_16x16x32_bf16 v[98:101], v[182:185], v[218:221], v[98:101]
	v_mfma_f32_16x16x32_bf16 v[86:89], v[160:163], v[226:229], v[86:89]
	v_mfma_f32_16x16x32_bf16 v[78:81], v[182:185], v[226:229], v[78:81]
	v_mfma_f32_16x16x32_bf16 v[70:73], v[160:163], v[234:237], v[70:73]
	v_mfma_f32_16x16x32_bf16 v[66:69], v[182:185], v[234:237], v[66:69]
	s_barrier
	s_setprio 0
	s_add_i32 s46, s48, s70
	v_lshl_add_u64 v[164:165], s[60:61], 0, v[166:167]
	s_mov_b32 m0, s46
	ds_read_b128 v[206:209], v188 offset:16384
	ds_read_b128 v[210:213], v188 offset:17408
	ds_read_b128 v[214:217], v188 offset:18432
	ds_read_b128 v[218:221], v188 offset:19456
	ds_read_b128 v[222:225], v188 offset:20480
	ds_read_b128 v[226:229], v188 offset:21504
	ds_read_b128 v[230:233], v188 offset:22528
	ds_read_b128 v[234:237], v188 offset:23552
	global_load_lds_dwordx4 v[164:165], off
	s_add_i32 m0, s46, 0x2000
	s_add_u32 s46, s60, 0x200000
	v_lshl_add_u64 v[242:243], s[60:61], 0, v[154:155]
	s_addc_u32 s47, s61, 0
	s_add_i32 s48, s49, s70
	global_load_lds_dwordx4 v[242:243], off
	v_lshl_add_u64 v[244:245], s[46:47], 0, v[166:167]
	s_mov_b32 m0, s48
	v_lshl_add_u64 v[246:247], s[64:65], 0, v[152:153]
	global_load_lds_dwordx4 v[244:245], off
	v_lshl_add_u64 v[244:245], s[46:47], 0, v[154:155]
	s_add_i32 m0, s48, 0x2000
	s_nop 0
	global_load_lds_dwordx4 v[244:245], off
	v_lshl_add_u64 v[244:245], s[64:65], 0, v[150:151]
	s_mov_b32 m0, s71
	s_nop 0
	global_load_lds_dwordx4 v[244:245], off
	s_mov_b32 m0, s72
	s_nop 0
	global_load_lds_dwordx4 v[246:247], off
	s_waitcnt vmcnt(8)
	s_waitcnt lgkmcnt(0)
	s_setprio 1
	s_waitcnt lgkmcnt(0)
	v_mfma_f32_16x16x32_bf16 v[62:65], v[130:133], v[206:209], v[62:65]
	v_mfma_f32_16x16x32_bf16 v[58:61], v[138:141], v[206:209], v[58:61]
	v_mfma_f32_16x16x32_bf16 v[50:53], v[130:133], v[214:217], v[50:53]
	v_mfma_f32_16x16x32_bf16 v[42:45], v[138:141], v[214:217], v[42:45]
	v_mfma_f32_16x16x32_bf16 v[34:37], v[130:133], v[222:225], v[34:37]
	v_mfma_f32_16x16x32_bf16 v[26:29], v[138:141], v[222:225], v[26:29]
	s_barrier
	v_mfma_f32_16x16x32_bf16 v[18:21], v[130:133], v[230:233], v[18:21]
	v_mfma_f32_16x16x32_bf16 v[10:13], v[138:141], v[230:233], v[10:13]
	v_mfma_f32_16x16x32_bf16 v[62:65], v[134:137], v[210:213], v[62:65]
	v_mfma_f32_16x16x32_bf16 v[58:61], v[142:145], v[210:213], v[58:61]
	v_mfma_f32_16x16x32_bf16 v[50:53], v[134:137], v[218:221], v[50:53]
	v_mfma_f32_16x16x32_bf16 v[42:45], v[142:145], v[218:221], v[42:45]
	v_mfma_f32_16x16x32_bf16 v[34:37], v[134:137], v[226:229], v[34:37]
	v_mfma_f32_16x16x32_bf16 v[26:29], v[142:145], v[226:229], v[26:29]
	v_mfma_f32_16x16x32_bf16 v[18:21], v[134:137], v[234:237], v[18:21]
	v_mfma_f32_16x16x32_bf16 v[10:13], v[142:145], v[234:237], v[10:13]
	v_mfma_f32_16x16x32_bf16 v[54:57], v[146:149], v[206:209], v[54:57]
	v_mfma_f32_16x16x32_bf16 v[46:49], v[178:181], v[206:209], v[46:49]
	v_mfma_f32_16x16x32_bf16 v[38:41], v[146:149], v[214:217], v[38:41]
	v_mfma_f32_16x16x32_bf16 v[30:33], v[178:181], v[214:217], v[30:33]
	v_mfma_f32_16x16x32_bf16 v[22:25], v[146:149], v[222:225], v[22:25]
	v_mfma_f32_16x16x32_bf16 v[14:17], v[178:181], v[222:225], v[14:17]
	v_mfma_f32_16x16x32_bf16 v[6:9], v[146:149], v[230:233], v[6:9]
	v_mfma_f32_16x16x32_bf16 v[2:5], v[178:181], v[230:233], v[2:5]
	v_mfma_f32_16x16x32_bf16 v[54:57], v[160:163], v[210:213], v[54:57]
	v_mfma_f32_16x16x32_bf16 v[46:49], v[182:185], v[210:213], v[46:49]
	v_mfma_f32_16x16x32_bf16 v[38:41], v[160:163], v[218:221], v[38:41]
	v_mfma_f32_16x16x32_bf16 v[30:33], v[182:185], v[218:221], v[30:33]
	v_mfma_f32_16x16x32_bf16 v[22:25], v[160:163], v[226:229], v[22:25]
	v_mfma_f32_16x16x32_bf16 v[14:17], v[182:185], v[226:229], v[14:17]
	v_mfma_f32_16x16x32_bf16 v[6:9], v[160:163], v[234:237], v[6:9]
	v_mfma_f32_16x16x32_bf16 v[2:5], v[182:185], v[234:237], v[2:5]
	s_barrier
	s_setprio 0
	s_add_i32 s48, 0, 0x18000
	s_add_i32 s49, 0, 0x1c000
	v_add_u32_e32 v142, s48, v186
	v_add_u32_e32 v182, s49, v186
	ds_read_b128 v[130:133], v142
	ds_read_b128 v[134:137], v142 offset:1024
	ds_read_b128 v[138:141], v142 offset:2048
	ds_read_b128 v[142:145], v142 offset:3072
	ds_read_b128 v[146:149], v182
	ds_read_b128 v[160:163], v182 offset:1024
	ds_read_b128 v[178:181], v182 offset:2048
	ds_read_b128 v[182:185], v182 offset:3072
	s_add_u32 s46, s64, 0x200000
	s_addc_u32 s47, s65, 0
	s_mov_b32 m0, s73
	v_lshl_add_u64 v[248:249], s[46:47], 0, v[150:151]
	ds_read_b128 v[206:209], v188 offset:32768
	ds_read_b128 v[210:213], v188 offset:33792
	ds_read_b128 v[214:217], v188 offset:34816
	ds_read_b128 v[218:221], v188 offset:35840
	ds_read_b128 v[222:225], v188 offset:36864
	ds_read_b128 v[226:229], v188 offset:37888
	ds_read_b128 v[230:233], v188 offset:38912
	ds_read_b128 v[234:237], v188 offset:39936
	global_load_lds_dwordx4 v[248:249], off
	v_lshl_add_u64 v[248:249], s[46:47], 0, v[152:153]
	s_mov_b32 m0, s74
	s_nop 0
	global_load_lds_dwordx4 v[248:249], off
	s_waitcnt vmcnt(8)
	s_waitcnt lgkmcnt(0)
	s_setprio 1
	s_waitcnt lgkmcnt(0)
	v_mfma_f32_16x16x32_bf16 v[126:129], v[130:133], v[206:209], v[126:129]
	v_mfma_f32_16x16x32_bf16 v[122:125], v[138:141], v[206:209], v[122:125]
	v_mfma_f32_16x16x32_bf16 v[118:121], v[130:133], v[214:217], v[118:121]
	v_mfma_f32_16x16x32_bf16 v[110:113], v[138:141], v[214:217], v[110:113]
	v_mfma_f32_16x16x32_bf16 v[94:97], v[130:133], v[222:225], v[94:97]
	v_mfma_f32_16x16x32_bf16 v[90:93], v[138:141], v[222:225], v[90:93]
	s_barrier
	v_mfma_f32_16x16x32_bf16 v[82:85], v[130:133], v[230:233], v[82:85]
	v_mfma_f32_16x16x32_bf16 v[74:77], v[138:141], v[230:233], v[74:77]
	v_mfma_f32_16x16x32_bf16 v[126:129], v[134:137], v[210:213], v[126:129]
	v_mfma_f32_16x16x32_bf16 v[122:125], v[142:145], v[210:213], v[122:125]
	v_mfma_f32_16x16x32_bf16 v[118:121], v[134:137], v[218:221], v[118:121]
	v_mfma_f32_16x16x32_bf16 v[110:113], v[142:145], v[218:221], v[110:113]
	v_mfma_f32_16x16x32_bf16 v[94:97], v[134:137], v[226:229], v[94:97]
	v_mfma_f32_16x16x32_bf16 v[90:93], v[142:145], v[226:229], v[90:93]
	v_mfma_f32_16x16x32_bf16 v[82:85], v[134:137], v[234:237], v[82:85]
	v_mfma_f32_16x16x32_bf16 v[74:77], v[142:145], v[234:237], v[74:77]
	v_mfma_f32_16x16x32_bf16 v[114:117], v[146:149], v[206:209], v[114:117]
	v_mfma_f32_16x16x32_bf16 v[106:109], v[178:181], v[206:209], v[106:109]
	v_mfma_f32_16x16x32_bf16 v[102:105], v[146:149], v[214:217], v[102:105]
	v_mfma_f32_16x16x32_bf16 v[98:101], v[178:181], v[214:217], v[98:101]
	v_mfma_f32_16x16x32_bf16 v[86:89], v[146:149], v[222:225], v[86:89]
	v_mfma_f32_16x16x32_bf16 v[78:81], v[178:181], v[222:225], v[78:81]
	v_mfma_f32_16x16x32_bf16 v[70:73], v[146:149], v[230:233], v[70:73]
	v_mfma_f32_16x16x32_bf16 v[66:69], v[178:181], v[230:233], v[66:69]
	v_mfma_f32_16x16x32_bf16 v[114:117], v[160:163], v[210:213], v[114:117]
	v_mfma_f32_16x16x32_bf16 v[106:109], v[182:185], v[210:213], v[106:109]
	v_mfma_f32_16x16x32_bf16 v[102:105], v[160:163], v[218:221], v[102:105]
	v_mfma_f32_16x16x32_bf16 v[98:101], v[182:185], v[218:221], v[98:101]
	v_mfma_f32_16x16x32_bf16 v[86:89], v[160:163], v[226:229], v[86:89]
	v_mfma_f32_16x16x32_bf16 v[78:81], v[182:185], v[226:229], v[78:81]
	v_mfma_f32_16x16x32_bf16 v[70:73], v[160:163], v[234:237], v[70:73]
	v_mfma_f32_16x16x32_bf16 v[66:69], v[182:185], v[234:237], v[66:69]
	s_barrier
	s_setprio 0
	s_add_i32 s46, s48, s70
	v_lshl_add_u64 v[164:165], v[164:165], 0, s[42:43]
	s_mov_b32 m0, s46
	ds_read_b128 v[206:209], v188 offset:49152
	ds_read_b128 v[210:213], v188 offset:50176
	ds_read_b128 v[214:217], v188 offset:51200
	ds_read_b128 v[218:221], v188 offset:52224
	ds_read_b128 v[222:225], v188 offset:53248
	ds_read_b128 v[226:229], v188 offset:54272
	ds_read_b128 v[230:233], v188 offset:55296
	ds_read_b128 v[234:237], v188 offset:56320
	global_load_lds_dwordx4 v[164:165], off
	s_add_i32 m0, s46, 0x2000
	s_add_u32 s46, s60, 0x200080
	v_lshl_add_u64 v[164:165], v[242:243], 0, s[42:43]
	s_addc_u32 s47, s61, 0
	s_add_i32 s48, s49, s70
	global_load_lds_dwordx4 v[164:165], off
	v_lshl_add_u64 v[164:165], s[46:47], 0, v[166:167]
	s_mov_b32 m0, s48
	s_nop 0
	global_load_lds_dwordx4 v[164:165], off
	v_lshl_add_u64 v[164:165], s[46:47], 0, v[154:155]
	s_add_i32 m0, s48, 0x2000
	s_nop 0
	global_load_lds_dwordx4 v[164:165], off
	v_lshl_add_u64 v[164:165], v[244:245], 0, s[42:43]
	s_mov_b32 m0, s75
	s_nop 0
	global_load_lds_dwordx4 v[164:165], off
	v_lshl_add_u64 v[164:165], v[246:247], 0, s[42:43]
	s_mov_b32 m0, s76
	s_nop 0
	global_load_lds_dwordx4 v[164:165], off
	s_waitcnt vmcnt(8)
	s_waitcnt lgkmcnt(0)
	s_setprio 1
	s_waitcnt lgkmcnt(0)
	v_mfma_f32_16x16x32_bf16 v[62:65], v[130:133], v[206:209], v[62:65]
	v_mfma_f32_16x16x32_bf16 v[58:61], v[138:141], v[206:209], v[58:61]
	v_mfma_f32_16x16x32_bf16 v[50:53], v[130:133], v[214:217], v[50:53]
	v_mfma_f32_16x16x32_bf16 v[42:45], v[138:141], v[214:217], v[42:45]
	v_mfma_f32_16x16x32_bf16 v[34:37], v[130:133], v[222:225], v[34:37]
	v_mfma_f32_16x16x32_bf16 v[26:29], v[138:141], v[222:225], v[26:29]
	s_barrier
	v_mfma_f32_16x16x32_bf16 v[18:21], v[130:133], v[230:233], v[18:21]
	v_mfma_f32_16x16x32_bf16 v[10:13], v[138:141], v[230:233], v[10:13]
	v_mfma_f32_16x16x32_bf16 v[62:65], v[134:137], v[210:213], v[62:65]
	v_mfma_f32_16x16x32_bf16 v[58:61], v[142:145], v[210:213], v[58:61]
	v_mfma_f32_16x16x32_bf16 v[50:53], v[134:137], v[218:221], v[50:53]
	v_mfma_f32_16x16x32_bf16 v[42:45], v[142:145], v[218:221], v[42:45]
	v_mfma_f32_16x16x32_bf16 v[34:37], v[134:137], v[226:229], v[34:37]
	v_mfma_f32_16x16x32_bf16 v[26:29], v[142:145], v[226:229], v[26:29]
	v_mfma_f32_16x16x32_bf16 v[18:21], v[134:137], v[234:237], v[18:21]
	v_mfma_f32_16x16x32_bf16 v[10:13], v[142:145], v[234:237], v[10:13]
	v_mfma_f32_16x16x32_bf16 v[54:57], v[146:149], v[206:209], v[54:57]
	v_mfma_f32_16x16x32_bf16 v[46:49], v[178:181], v[206:209], v[46:49]
	v_mfma_f32_16x16x32_bf16 v[38:41], v[146:149], v[214:217], v[38:41]
	v_mfma_f32_16x16x32_bf16 v[30:33], v[178:181], v[214:217], v[30:33]
	v_mfma_f32_16x16x32_bf16 v[22:25], v[146:149], v[222:225], v[22:25]
	v_mfma_f32_16x16x32_bf16 v[14:17], v[178:181], v[222:225], v[14:17]
	v_mfma_f32_16x16x32_bf16 v[6:9], v[146:149], v[230:233], v[6:9]
	v_mfma_f32_16x16x32_bf16 v[2:5], v[178:181], v[230:233], v[2:5]
	v_mfma_f32_16x16x32_bf16 v[54:57], v[160:163], v[210:213], v[54:57]
	v_mfma_f32_16x16x32_bf16 v[46:49], v[182:185], v[210:213], v[46:49]
	v_mfma_f32_16x16x32_bf16 v[38:41], v[160:163], v[218:221], v[38:41]
	v_mfma_f32_16x16x32_bf16 v[30:33], v[182:185], v[218:221], v[30:33]
	v_mfma_f32_16x16x32_bf16 v[22:25], v[160:163], v[226:229], v[22:25]
	v_mfma_f32_16x16x32_bf16 v[14:17], v[182:185], v[226:229], v[14:17]
	v_mfma_f32_16x16x32_bf16 v[6:9], v[160:163], v[234:237], v[6:9]
	v_mfma_f32_16x16x32_bf16 v[2:5], v[182:185], v[234:237], v[2:5]
	s_barrier
	s_setprio 0
	s_add_i32 s82, s82, 2
	s_add_u32 s62, s62, 0x100
	s_addc_u32 s63, s63, 0
	s_add_u32 s80, s80, 0x100
	s_addc_u32 s81, s81, 0
	s_cmpk_gt_u32 s82, 0x7d
	s_cbranch_scc0 .LBB0_1138
	s_and_b64 vcc, exec, s[10:11]
	s_cbranch_vccz .LBB0_1141
	s_barrier
